# scan0 chunk loops: half-wave lane-15 broadcast (x - x[15]) via two masked DPP ops (row_newbcast:15 / row_bcast:15) instead of ds_bpermute + serialized lgkm waits (bit-identical)
# baseline (speedup 1.0000x reference)
.LBB0_855:
	s_and_saveexec_b64 s[96:97], vcc
	s_cbranch_execz .LBB0_859
	s_waitcnt vmcnt(8)
	v_cvt_f32_f16_e32 v76, v24
	v_cvt_f32_f16_sdwa v75, v24 dst_sel:DWORD dst_unused:UNUSED_PAD src0_sel:WORD_1
	v_cvt_f32_f16_e32 v74, v25
	v_cvt_f32_f16_sdwa v73, v25 dst_sel:DWORD dst_unused:UNUSED_PAD src0_sel:WORD_1
	v_add_f32_dpp v0, v76, v76 row_shr:1 row_mask:0xf bank_mask:0xf bound_ctrl:1
	v_add_f32_dpp v1, v75, v75 row_shr:1 row_mask:0xf bank_mask:0xf bound_ctrl:1
	v_mov_b32_e32 v62, v2
	v_add_f32_dpp v0, v0, v0 row_shr:2 row_mask:0xf bank_mask:0xf bound_ctrl:1
	v_add_f32_dpp v1, v1, v1 row_shr:2 row_mask:0xf bank_mask:0xf bound_ctrl:1
	v_cvt_f32_f16_e32 v72, v26
	v_add_f32_dpp v0, v0, v0 row_shr:4 row_mask:0xf bank_mask:0xf bound_ctrl:1
	v_add_f32_dpp v24, v74, v74 row_shr:1 row_mask:0xf bank_mask:0xf bound_ctrl:1
	v_add_f32_dpp v1, v1, v1 row_shr:4 row_mask:0xf bank_mask:0xf bound_ctrl:1
	v_add_f32_dpp v0, v0, v0 row_shr:8 row_mask:0xf bank_mask:0xf bound_ctrl:1
	v_add_f32_dpp v24, v24, v24 row_shr:2 row_mask:0xf bank_mask:0xf bound_ctrl:1
	v_add_f32_dpp v1, v1, v1 row_shr:8 row_mask:0xf bank_mask:0xf bound_ctrl:1
	v_mov_b32_dpp v62, v0 row_bcast:15 row_mask:0xa bank_mask:0xf
	v_add_f32_e32 v78, v0, v62
	v_mov_b32_e32 v0, v2
	v_cvt_f32_f16_sdwa v71, v26 dst_sel:DWORD dst_unused:UNUSED_PAD src0_sel:WORD_1
	v_add_f32_dpp v25, v73, v73 row_shr:1 row_mask:0xf bank_mask:0xf bound_ctrl:1
	v_add_f32_dpp v24, v24, v24 row_shr:4 row_mask:0xf bank_mask:0xf bound_ctrl:1
	v_mov_b32_dpp v0, v1 row_bcast:15 row_mask:0xa bank_mask:0xf
	v_add_f32_dpp v25, v25, v25 row_shr:2 row_mask:0xf bank_mask:0xf bound_ctrl:1
	v_add_f32_dpp v24, v24, v24 row_shr:8 row_mask:0xf bank_mask:0xf bound_ctrl:1
	v_add_f32_e32 v79, v1, v0
	v_mov_b32_e32 v0, v2
	v_cvt_f32_f16_e32 v70, v27
	v_add_f32_dpp v26, v72, v72 row_shr:1 row_mask:0xf bank_mask:0xf bound_ctrl:1
	v_add_f32_dpp v25, v25, v25 row_shr:4 row_mask:0xf bank_mask:0xf bound_ctrl:1
	v_mov_b32_dpp v0, v24 row_bcast:15 row_mask:0xa bank_mask:0xf
	v_add_f32_dpp v26, v26, v26 row_shr:2 row_mask:0xf bank_mask:0xf bound_ctrl:1
	v_add_f32_dpp v25, v25, v25 row_shr:8 row_mask:0xf bank_mask:0xf bound_ctrl:1
	v_add_f32_e32 v80, v24, v0
	v_mov_b32_e32 v0, v2
	v_cvt_f32_f16_sdwa v3, v27 dst_sel:DWORD dst_unused:UNUSED_PAD src0_sel:WORD_1
	v_add_f32_dpp v27, v71, v71 row_shr:1 row_mask:0xf bank_mask:0xf bound_ctrl:1
	v_add_f32_dpp v26, v26, v26 row_shr:4 row_mask:0xf bank_mask:0xf bound_ctrl:1
	v_mov_b32_dpp v0, v25 row_bcast:15 row_mask:0xa bank_mask:0xf
	v_add_f32_dpp v27, v27, v27 row_shr:2 row_mask:0xf bank_mask:0xf bound_ctrl:1
	v_add_f32_dpp v26, v26, v26 row_shr:8 row_mask:0xf bank_mask:0xf bound_ctrl:1
	v_add_f32_e32 v81, v25, v0
	v_mov_b32_e32 v0, v2
	v_add_f32_dpp v60, v70, v70 row_shr:1 row_mask:0xf bank_mask:0xf bound_ctrl:1
	v_add_f32_dpp v27, v27, v27 row_shr:4 row_mask:0xf bank_mask:0xf bound_ctrl:1
	v_mov_b32_dpp v0, v26 row_bcast:15 row_mask:0xa bank_mask:0xf
	v_add_f32_dpp v60, v60, v60 row_shr:2 row_mask:0xf bank_mask:0xf bound_ctrl:1
	v_add_f32_dpp v27, v27, v27 row_shr:8 row_mask:0xf bank_mask:0xf bound_ctrl:1
	v_add_f32_e32 v77, v26, v0
	v_mov_b32_e32 v0, v2
	v_add_f32_dpp v60, v60, v60 row_shr:4 row_mask:0xf bank_mask:0xf bound_ctrl:1
	v_add_f32_dpp v61, v3, v3 row_shr:1 row_mask:0xf bank_mask:0xf bound_ctrl:1
	v_mov_b32_dpp v0, v27 row_bcast:15 row_mask:0xa bank_mask:0xf
	v_add_f32_dpp v60, v60, v60 row_shr:8 row_mask:0xf bank_mask:0xf bound_ctrl:1
	v_add_f32_e32 v82, v27, v0
	v_mov_b32_e32 v0, v2
	v_add_f32_dpp v61, v61, v61 row_shr:2 row_mask:0xf bank_mask:0xf bound_ctrl:1
	v_mov_b32_dpp v0, v60 row_bcast:15 row_mask:0xa bank_mask:0xf
	v_add_f32_e32 v83, v60, v0
	s_waitcnt lgkmcnt(0)
	s_nop 1
	v_subrev_f32_dpp v0, v78, v78 row_newbcast:15 row_mask:0x5 bank_mask:0xf
	v_subrev_f32_dpp v0, v78, v78 row_bcast:15 row_mask:0xa bank_mask:0xf
	v_med3_f32 v0, v0, s69, v189
	v_add_f32_dpp v61, v61, v61 row_shr:4 row_mask:0xf bank_mask:0xf bound_ctrl:1
	v_mul_f32_e32 v0, 0x3fb8aa3b, v0
	v_exp_f32_e32 v24, v0
	v_add_f32_dpp v61, v61, v61 row_shr:8 row_mask:0xf bank_mask:0xf bound_ctrl:1
	v_mov_b32_e32 v0, v2
	s_nop 1
	v_subrev_f32_dpp v1, v79, v79 row_newbcast:15 row_mask:0x5 bank_mask:0xf
	v_subrev_f32_dpp v1, v79, v79 row_bcast:15 row_mask:0xa bank_mask:0xf
	v_med3_f32 v1, v1, s69, v189
	v_mov_b32_dpp v0, v61 row_bcast:15 row_mask:0xa bank_mask:0xf
	v_add_f32_e32 v84, v61, v0
	v_mul_f32_e32 v1, 0x3fb8aa3b, v1
	v_exp_f32_e32 v25, v1
	s_nop 1
	v_subrev_f32_dpp v26, v80, v80 row_newbcast:15 row_mask:0x5 bank_mask:0xf
	v_subrev_f32_dpp v26, v80, v80 row_bcast:15 row_mask:0xa bank_mask:0xf
	s_nop 1
	v_subrev_f32_dpp v1, v81, v81 row_newbcast:15 row_mask:0x5 bank_mask:0xf
	v_subrev_f32_dpp v1, v81, v81 row_bcast:15 row_mask:0xa bank_mask:0xf
	s_nop 1
	v_subrev_f32_dpp v62, v77, v77 row_newbcast:15 row_mask:0x5 bank_mask:0xf
	v_subrev_f32_dpp v62, v77, v77 row_bcast:15 row_mask:0xa bank_mask:0xf
	s_nop 1
	v_subrev_f32_dpp v63, v82, v82 row_newbcast:15 row_mask:0x5 bank_mask:0xf
	v_subrev_f32_dpp v63, v82, v82 row_bcast:15 row_mask:0xa bank_mask:0xf
	s_nop 1
	v_subrev_f32_dpp v64, v83, v83 row_newbcast:15 row_mask:0x5 bank_mask:0xf
	v_subrev_f32_dpp v64, v83, v83 row_bcast:15 row_mask:0xa bank_mask:0xf
	s_nop 1
	v_subrev_f32_dpp v65, v84, v84 row_newbcast:15 row_mask:0x5 bank_mask:0xf
	v_subrev_f32_dpp v65, v84, v84 row_bcast:15 row_mask:0xa bank_mask:0xf
	v_med3_f32 v26, v26, s69, v189
	v_med3_f32 v1, v1, s69, v189
	v_med3_f32 v62, v62, s69, v189
	v_med3_f32 v63, v63, s69, v189
	v_med3_f32 v64, v64, s69, v189
	v_med3_f32 v65, v65, s69, v189
	v_mul_f32_e32 v26, 0x3fb8aa3b, v26
	v_mul_f32_e32 v1, 0x3fb8aa3b, v1
	v_mul_f32_e32 v62, 0x3fb8aa3b, v62
	v_mul_f32_e32 v63, 0x3fb8aa3b, v63
	v_mul_f32_e32 v64, 0x3fb8aa3b, v64
	v_mul_f32_e32 v65, 0x3fb8aa3b, v65
	v_exp_f32_e32 v60, v26
	v_exp_f32_e32 v61, v1
	v_exp_f32_e32 v62, v62
	v_exp_f32_e32 v63, v63
	v_exp_f32_e32 v64, v64
	v_exp_f32_e32 v65, v65
	ds_bpermute_b32 v0, v194, v24
	ds_bpermute_b32 v1, v194, v25
	ds_bpermute_b32 v26, v194, v60
	ds_bpermute_b32 v27, v194, v61
	ds_bpermute_b32 v68, v194, v62
	ds_bpermute_b32 v69, v194, v63
	ds_bpermute_b32 v66, v194, v64
	ds_bpermute_b32 v67, v194, v65
	s_and_saveexec_b64 s[16:17], s[6:7]
	s_cbranch_execz .LBB0_858
	v_mul_f32_e32 v78, 0x3fb8aa3b, v78
	v_mul_f32_e32 v79, 0x3fb8aa3b, v79
	v_mul_f32_e32 v80, 0x3fb8aa3b, v80
	v_mul_f32_e32 v81, 0x3fb8aa3b, v81
	v_exp_f32_e32 v78, v78
	v_exp_f32_e32 v79, v79
	v_exp_f32_e32 v80, v80
	v_exp_f32_e32 v81, v81
	v_mul_f32_e32 v77, 0x3fb8aa3b, v77
	ds_write_b128 v195, v[78:81] offset:34816
	v_exp_f32_e32 v78, v77
	v_mul_f32_e32 v77, 0x3fb8aa3b, v82
	v_exp_f32_e32 v79, v77
	v_mul_f32_e32 v77, 0x3fb8aa3b, v83
	v_exp_f32_e32 v80, v77
	v_mul_f32_e32 v77, 0x3fb8aa3b, v84
	v_exp_f32_e32 v81, v77
	ds_write_b128 v195, v[78:81] offset:34832

.LBB0_859:
	s_or_b64 exec, exec, s[96:97]
	s_add_i32 s78, s77, -1
	s_min_i32 s16, s78, s3
	s_lshl_b32 s16, s16, 5
	v_or_b32_e32 v0, s16, v191
	v_xad_u32 v1, v0, -1, s74
	v_cndmask_b32_e64 v0, v1, v0, s[4:5]
	v_add_u32_e32 v1, s16, v192
	v_xad_u32 v3, v1, -1, s74
	v_add_u32_e32 v0, s73, v0
	v_cndmask_b32_e64 v3, v3, v1, s[4:5]
	v_ashrrev_i32_e32 v1, 31, v0
	s_waitcnt vmcnt(7)
	ds_write_b128 v197, v[8:11] offset:26112
	v_mad_i64_i32 v[8:9], s[16:17], v0, s89, v[180:181]
	v_lshlrev_b64 v[0:1], 11, v[0:1]
	v_lshl_add_u64 v[0:1], v[182:183], 0, v[0:1]
	global_load_dwordx4 v[16:19], v[8:9], off
	global_load_dwordx4 v[24:27], v[0:1], off
	v_add_u32_e32 v0, s73, v3
	v_mad_i64_i32 v[0:1], s[16:17], v0, s89, v[184:185]
	global_load_dwordx4 v[8:11], v[0:1], off
	s_waitcnt lgkmcnt(0)
	s_barrier
	ds_read_b64_tr_b16 v[92:93], v199 offset:26112
	ds_read_b64_tr_b16 v[94:95], v199 offset:30464
	ds_read_b64 v[88:89], v200
	ds_read_b64 v[90:91], v200 offset:32
	ds_read_b64 v[80:81], v200 offset:64
	ds_read_b64 v[82:83], v200 offset:96
	ds_read_b64 v[72:73], v200 offset:128
	ds_read_b64 v[74:75], v200 offset:160
	ds_read_b64 v[60:61], v200 offset:192
	ds_read_b64 v[62:63], v200 offset:224
	ds_read_b64 v[84:85], v200 offset:4352
	ds_read_b64 v[86:87], v200 offset:4384
	ds_read_b64 v[76:77], v200 offset:4416
	ds_read_b64 v[78:79], v200 offset:4448
	ds_read_b64 v[68:69], v200 offset:4480
	ds_read_b64 v[70:71], v200 offset:4512
	ds_read_b64 v[64:65], v200 offset:4544
	ds_read_b64 v[66:67], v200 offset:4576
	ds_read_b64 v[100:101], v201 offset:13056
	ds_read_b64 v[102:103], v201 offset:13088
	ds_read_b64 v[96:97], v201 offset:8704
	ds_read_b64 v[98:99], v201 offset:8736
	ds_read_b64 v[108:109], v201 offset:8768
	ds_read_b64 v[110:111], v201 offset:8800
	ds_read_b64 v[112:113], v201 offset:13120
	ds_read_b64 v[114:115], v201 offset:13152
	s_waitcnt lgkmcnt(6)
	v_mfma_f32_16x16x32_bf16 v[100:103], v[100:103], v[84:87], 0
	s_waitcnt lgkmcnt(4)
	v_mfma_f32_16x16x32_bf16 v[104:107], v[96:99], v[88:91], 0
	s_waitcnt lgkmcnt(0)
	v_mfma_f32_16x16x32_bf16 v[100:103], v[112:115], v[76:79], v[100:103]
	ds_read_b64 v[112:113], v201 offset:8832
	ds_read_b64 v[114:115], v201 offset:8864
	ds_read_b64 v[116:117], v201 offset:13184
	ds_read_b64 v[118:119], v201 offset:13216
	v_mfma_f32_16x16x32_bf16 v[104:107], v[108:111], v[80:83], v[104:107]
	s_waitcnt lgkmcnt(0)
	v_mfma_f32_16x16x32_bf16 v[100:103], v[116:119], v[68:71], v[100:103]
	ds_read_b64 v[116:117], v201 offset:8896
	ds_read_b64 v[118:119], v201 offset:8928
	ds_read_b64 v[226:227], v201 offset:13248
	ds_read_b64 v[228:229], v201 offset:13280
	v_mov_b32_e32 v0, s93
	v_mfma_f32_16x16x32_bf16 v[96:99], v[96:99], v[84:87], 0
	v_mfma_f32_16x16x32_bf16 v[104:107], v[112:115], v[72:75], v[104:107]
	v_mfma_f32_16x16x32_bf16 v[96:99], v[108:111], v[76:79], v[96:99]
	s_waitcnt lgkmcnt(2)
	v_mfma_f32_16x16x32_bf16 v[104:107], v[116:119], v[60:63], v[104:107]
	s_waitcnt lgkmcnt(0)
	v_mfma_f32_16x16x32_bf16 v[100:103], v[226:229], v[64:67], v[100:103]
	v_mov_b32_e32 v226, s93
	s_nop 4
	v_cndmask_b32_e64 v0, v104, v0, s[8:9]
	v_cndmask_b32_e64 v0, v0, v104, s[10:11]
	v_mfma_f32_16x16x32_bf16 v[96:99], v[112:115], v[68:71], v[96:99]
	v_cndmask_b32_e64 v3, v106, 0, s[12:13]
	v_cndmask_b32_e64 v1, v100, v226, s[8:9]
	v_cndmask_b32_e64 v100, v1, v100, s[10:11]
	v_cndmask_b32_e64 v1, 0, v105, s[10:11]
	v_cndmask_b32_e64 v104, v107, 0, s[14:15]
	v_cvt_pk_bf16_f32 v0, v0, v1
	v_cvt_pk_bf16_f32 v1, v3, v104
	ds_read_b128 v[104:107], v202 offset:35328
	ds_read_b128 v[108:111], v202 offset:35392
	v_mfma_f32_16x16x32_bf16 v[96:99], v[116:119], v[64:67], v[96:99]
	v_cndmask_b32_e64 v101, 0, v101, s[10:11]
	v_cndmask_b32_e64 v102, v102, 0, s[12:13]
	v_cndmask_b32_e64 v103, v103, 0, s[14:15]
	v_mov_b32_e32 v3, v2
	s_waitcnt lgkmcnt(0)
	v_pk_mul_f32 v[110:111], v[54:55], v[110:111]
	s_nop 1
	v_cvt_pk_bf16_f32 v96, v96, v97
	v_cvt_pk_bf16_f32 v97, v98, v99
	v_cvt_pk_bf16_f32 v98, v100, v101
	v_cvt_pk_bf16_f32 v99, v102, v103
	v_mfma_f32_16x16x32_bf16 v[100:103], v[92:95], v[0:3], 0
	v_mul_f32_e64 v0, v58, v106
	v_mul_f32_e64 v1, v59, v107
	v_pk_mul_f32 v[106:107], v[52:53], v[108:109]
	v_pk_mul_f32 v[104:105], v[56:57], v[104:105]
	v_cvt_pk_bf16_f32 v106, v106, v107
	v_cvt_pk_bf16_f32 v107, v110, v111
	ds_read_b128 v[108:111], v202 offset:35456
	ds_read_b128 v[112:115], v202 offset:35520
	v_cvt_pk_bf16_f32 v104, v104, v105
	v_cvt_pk_bf16_f32 v105, v0, v1
	v_mfma_f32_16x16x32_bf16 v[96:99], v[92:95], v[96:99], 0
	s_waitcnt lgkmcnt(1)
	v_pk_mul_f32 v[0:1], v[50:51], v[110:111]
	v_pk_mul_f32 v[108:109], v[48:49], v[108:109]
	s_waitcnt lgkmcnt(0)
	v_pk_mul_f32 v[110:111], v[46:47], v[114:115]
	v_pk_mul_f32 v[112:113], v[44:45], v[112:113]
	v_cvt_pk_bf16_f32 v116, v108, v109
	v_cvt_pk_bf16_f32 v118, v112, v113
	v_cvt_pk_bf16_f32 v119, v110, v111
	ds_read_b128 v[108:111], v202 offset:35584
	ds_read_b128 v[112:115], v202 offset:35648
	v_cvt_pk_bf16_f32 v117, v0, v1
	v_mfma_f32_16x16x32_bf16 v[88:91], v[104:107], v[88:91], v[100:103]
	v_cndmask_b32_e64 v3, v222, v190, s[4:5]
	s_waitcnt lgkmcnt(1)
	v_pk_mul_f32 v[0:1], v[42:43], v[110:111]
	s_waitcnt lgkmcnt(0)
	v_pk_mul_f32 v[114:115], v[38:39], v[114:115]
	v_pk_mul_f32 v[110:111], v[36:37], v[112:113]
	v_pk_mul_f32 v[108:109], v[40:41], v[108:109]
	v_cvt_pk_bf16_f32 v110, v110, v111
	v_cvt_pk_bf16_f32 v111, v114, v115
	ds_read_b128 v[112:115], v202 offset:35712
	ds_read_b128 v[226:229], v202 offset:35776
	v_cvt_pk_bf16_f32 v108, v108, v109
	v_cvt_pk_bf16_f32 v109, v0, v1
	v_mfma_f32_16x16x32_bf16 v[84:87], v[104:107], v[84:87], v[96:99]
	s_waitcnt lgkmcnt(1)
	v_pk_mul_f32 v[0:1], v[34:35], v[114:115]
	s_waitcnt lgkmcnt(0)
	v_pk_mul_f32 v[228:229], v[30:31], v[228:229]
	v_pk_mul_f32 v[114:115], v[28:29], v[226:227]
	v_mfma_f32_16x16x32_bf16 v[80:83], v[116:119], v[80:83], v[88:91]
	v_cvt_pk_bf16_f32 v114, v114, v115
	v_cvt_pk_bf16_f32 v115, v228, v229
	ds_read_b128 v[226:229], v202 offset:34816
	ds_read_b64_tr_b16 v[232:233], v198 offset:21760
	ds_read_b64_tr_b16 v[230:231], v198 offset:17408
	ds_read_b64_tr_b16 v[234:235], v198 offset:17440
	v_pk_mul_f32 v[112:113], v[32:33], v[112:113]
	s_waitcnt lgkmcnt(3)
	v_pk_mul_f32 v[58:59], v[58:59], v[228:229]
	v_pk_mul_f32 v[56:57], v[56:57], v[226:227]
	ds_read_b128 v[226:229], v202 offset:34880
	ds_read_b64_tr_b16 v[236:237], v198 offset:21792
	s_waitcnt lgkmcnt(3)
	v_mfma_f32_16x16x32_bf16 v[56:59], v[230:233], v[92:95], v[56:59]
	v_cvt_pk_bf16_f32 v112, v112, v113
	v_cvt_pk_bf16_f32 v113, v0, v1
	s_waitcnt lgkmcnt(1)
	v_pk_mul_f32 v[54:55], v[54:55], v[228:229]
	v_pk_mul_f32 v[52:53], v[52:53], v[226:227]
	ds_read_b128 v[226:229], v202 offset:34944
	ds_read_b64_tr_b16 v[230:231], v198 offset:17472
	ds_read_b64_tr_b16 v[232:233], v198 offset:21824
	v_mfma_f32_16x16x32_bf16 v[76:79], v[116:119], v[76:79], v[84:87]
	v_xor_b32_e32 v1, 0xffffffef, v190
	s_waitcnt lgkmcnt(2)
	v_pk_mul_f32 v[50:51], v[50:51], v[228:229]
	v_pk_mul_f32 v[48:49], v[48:49], v[226:227]
	v_mfma_f32_16x16x32_bf16 v[72:75], v[108:111], v[72:75], v[80:83]
	v_add_u32_e32 v0, 16, v190
	v_add_u32_e32 v1, s74, v1
	s_waitcnt lgkmcnt(0)
	v_mfma_f32_16x16x32_bf16 v[48:51], v[230:233], v[92:95], v[48:51]
	ds_read_b128 v[226:229], v202 offset:35008
	ds_read_b64_tr_b16 v[230:231], v198 offset:17504
	ds_read_b64_tr_b16 v[232:233], v198 offset:21856
	s_waitcnt lgkmcnt(2)
	v_pk_mul_f32 v[46:47], v[46:47], v[228:229]
	v_pk_mul_f32 v[44:45], v[44:45], v[226:227]
	v_mfma_f32_16x16x32_bf16 v[68:71], v[108:111], v[68:71], v[76:79]
	s_waitcnt lgkmcnt(0)
	v_mfma_f32_16x16x32_bf16 v[44:47], v[230:233], v[92:95], v[44:47]
	ds_read_b128 v[226:229], v202 offset:35072
	ds_read_b64_tr_b16 v[230:231], v198 offset:17536
	ds_read_b64_tr_b16 v[232:233], v198 offset:21888
	s_waitcnt lgkmcnt(2)
	v_pk_mul_f32 v[42:43], v[42:43], v[228:229]
	v_pk_mul_f32 v[40:41], v[40:41], v[226:227]
	v_mfma_f32_16x16x32_bf16 v[60:63], v[112:115], v[60:63], v[72:75]
	s_waitcnt lgkmcnt(0)
	v_mfma_f32_16x16x32_bf16 v[40:43], v[230:233], v[92:95], v[40:43]
	ds_read_b128 v[226:229], v202 offset:35136
	ds_read_b64_tr_b16 v[230:231], v198 offset:17568
	ds_read_b64_tr_b16 v[232:233], v198 offset:21920
	s_waitcnt lgkmcnt(2)
	v_pk_mul_f32 v[38:39], v[38:39], v[228:229]
	v_pk_mul_f32 v[36:37], v[36:37], v[226:227]
	v_mfma_f32_16x16x32_bf16 v[64:67], v[112:115], v[64:67], v[68:71]
	s_waitcnt lgkmcnt(0)
	v_mfma_f32_16x16x32_bf16 v[36:39], v[230:233], v[92:95], v[36:39]
	ds_read_b128 v[226:229], v202 offset:35200
	ds_read_b64_tr_b16 v[230:231], v198 offset:17600
	ds_read_b64_tr_b16 v[232:233], v198 offset:21952
	v_cndmask_b32_e64 v68, v1, v0, s[4:5]
	v_cvt_pk_bf16_f32 v1, v62, v63
	s_waitcnt lgkmcnt(2)
	v_pk_mul_f32 v[34:35], v[34:35], v[228:229]
	v_pk_mul_f32 v[32:33], v[32:33], v[226:227]
	v_add_u32_e32 v62, s73, v3
	v_ashrrev_i32_e32 v63, 31, v62
	s_waitcnt lgkmcnt(0)
	v_mfma_f32_16x16x32_bf16 v[32:35], v[230:233], v[92:95], v[32:35]
	ds_read_b128 v[226:229], v202 offset:35264
	ds_read_b64_tr_b16 v[230:231], v198 offset:17632
	ds_read_b64_tr_b16 v[232:233], v198 offset:21984
	v_lshlrev_b64 v[62:63], 11, v[62:63]
	v_cvt_pk_bf16_f32 v0, v60, v61
	s_waitcnt lgkmcnt(2)
	v_pk_mul_f32 v[30:31], v[30:31], v[228:229]
	v_pk_mul_f32 v[28:29], v[28:29], v[226:227]
	v_lshl_add_u64 v[62:63], v[186:187], 0, v[62:63]
	v_mfma_f32_16x16x32_bf16 v[52:55], v[234:237], v[92:95], v[52:55]
	global_store_dwordx2 v[62:63], v[0:1], off
	v_add_u32_e32 v0, s73, v68
	v_ashrrev_i32_e32 v1, 31, v0
	s_waitcnt lgkmcnt(0)
	v_mfma_f32_16x16x32_bf16 v[28:31], v[230:233], v[92:95], v[28:31]
	v_lshlrev_b64 v[0:1], 11, v[0:1]
	v_cvt_pk_bf16_f32 v60, v64, v65
	v_cvt_pk_bf16_f32 v61, v66, v67
	v_lshl_add_u64 v[0:1], v[186:187], 0, v[0:1]
	global_store_dwordx2 v[0:1], v[60:61], off
	s_and_saveexec_b64 s[96:97], vcc
	s_cbranch_execz .LBB0_854
	s_waitcnt vmcnt(8)
	v_cvt_f32_f16_e32 v76, v20
	v_cvt_f32_f16_sdwa v75, v20 dst_sel:DWORD dst_unused:UNUSED_PAD src0_sel:WORD_1
	v_cvt_f32_f16_e32 v74, v21
	v_cvt_f32_f16_sdwa v73, v21 dst_sel:DWORD dst_unused:UNUSED_PAD src0_sel:WORD_1
	v_add_f32_dpp v0, v76, v76 row_shr:1 row_mask:0xf bank_mask:0xf bound_ctrl:1
	v_add_f32_dpp v1, v75, v75 row_shr:1 row_mask:0xf bank_mask:0xf bound_ctrl:1
	v_mov_b32_e32 v62, v2
	v_add_f32_dpp v0, v0, v0 row_shr:2 row_mask:0xf bank_mask:0xf bound_ctrl:1
	v_add_f32_dpp v1, v1, v1 row_shr:2 row_mask:0xf bank_mask:0xf bound_ctrl:1
	v_cvt_f32_f16_e32 v72, v22
	v_add_f32_dpp v0, v0, v0 row_shr:4 row_mask:0xf bank_mask:0xf bound_ctrl:1
	v_add_f32_dpp v20, v74, v74 row_shr:1 row_mask:0xf bank_mask:0xf bound_ctrl:1
	v_add_f32_dpp v1, v1, v1 row_shr:4 row_mask:0xf bank_mask:0xf bound_ctrl:1
	v_add_f32_dpp v0, v0, v0 row_shr:8 row_mask:0xf bank_mask:0xf bound_ctrl:1
	v_add_f32_dpp v20, v20, v20 row_shr:2 row_mask:0xf bank_mask:0xf bound_ctrl:1
	v_add_f32_dpp v1, v1, v1 row_shr:8 row_mask:0xf bank_mask:0xf bound_ctrl:1
	v_mov_b32_dpp v62, v0 row_bcast:15 row_mask:0xa bank_mask:0xf
	v_add_f32_e32 v78, v0, v62
	v_mov_b32_e32 v0, v2
	v_cvt_f32_f16_sdwa v71, v22 dst_sel:DWORD dst_unused:UNUSED_PAD src0_sel:WORD_1
	v_add_f32_dpp v21, v73, v73 row_shr:1 row_mask:0xf bank_mask:0xf bound_ctrl:1
	v_add_f32_dpp v20, v20, v20 row_shr:4 row_mask:0xf bank_mask:0xf bound_ctrl:1
	v_mov_b32_dpp v0, v1 row_bcast:15 row_mask:0xa bank_mask:0xf
	v_add_f32_dpp v21, v21, v21 row_shr:2 row_mask:0xf bank_mask:0xf bound_ctrl:1
	v_add_f32_dpp v20, v20, v20 row_shr:8 row_mask:0xf bank_mask:0xf bound_ctrl:1
	v_add_f32_e32 v79, v1, v0
	v_mov_b32_e32 v0, v2
	v_cvt_f32_f16_e32 v70, v23
	v_add_f32_dpp v22, v72, v72 row_shr:1 row_mask:0xf bank_mask:0xf bound_ctrl:1
	v_add_f32_dpp v21, v21, v21 row_shr:4 row_mask:0xf bank_mask:0xf bound_ctrl:1
	v_mov_b32_dpp v0, v20 row_bcast:15 row_mask:0xa bank_mask:0xf
	v_add_f32_dpp v22, v22, v22 row_shr:2 row_mask:0xf bank_mask:0xf bound_ctrl:1
	v_add_f32_dpp v21, v21, v21 row_shr:8 row_mask:0xf bank_mask:0xf bound_ctrl:1
	v_add_f32_e32 v80, v20, v0
	v_mov_b32_e32 v0, v2
	v_cvt_f32_f16_sdwa v3, v23 dst_sel:DWORD dst_unused:UNUSED_PAD src0_sel:WORD_1
	v_add_f32_dpp v23, v71, v71 row_shr:1 row_mask:0xf bank_mask:0xf bound_ctrl:1
	v_add_f32_dpp v22, v22, v22 row_shr:4 row_mask:0xf bank_mask:0xf bound_ctrl:1
	v_mov_b32_dpp v0, v21 row_bcast:15 row_mask:0xa bank_mask:0xf
	v_add_f32_dpp v23, v23, v23 row_shr:2 row_mask:0xf bank_mask:0xf bound_ctrl:1
	v_add_f32_dpp v22, v22, v22 row_shr:8 row_mask:0xf bank_mask:0xf bound_ctrl:1
	v_add_f32_e32 v81, v21, v0
	v_mov_b32_e32 v0, v2
	v_add_f32_dpp v60, v70, v70 row_shr:1 row_mask:0xf bank_mask:0xf bound_ctrl:1
	v_add_f32_dpp v23, v23, v23 row_shr:4 row_mask:0xf bank_mask:0xf bound_ctrl:1
	v_mov_b32_dpp v0, v22 row_bcast:15 row_mask:0xa bank_mask:0xf
	v_add_f32_dpp v60, v60, v60 row_shr:2 row_mask:0xf bank_mask:0xf bound_ctrl:1
	v_add_f32_dpp v23, v23, v23 row_shr:8 row_mask:0xf bank_mask:0xf bound_ctrl:1
	v_add_f32_e32 v77, v22, v0
	v_mov_b32_e32 v0, v2
	v_add_f32_dpp v60, v60, v60 row_shr:4 row_mask:0xf bank_mask:0xf bound_ctrl:1
	v_add_f32_dpp v61, v3, v3 row_shr:1 row_mask:0xf bank_mask:0xf bound_ctrl:1
	v_mov_b32_dpp v0, v23 row_bcast:15 row_mask:0xa bank_mask:0xf
	v_add_f32_dpp v60, v60, v60 row_shr:8 row_mask:0xf bank_mask:0xf bound_ctrl:1
	v_add_f32_e32 v82, v23, v0
	v_mov_b32_e32 v0, v2
	v_add_f32_dpp v61, v61, v61 row_shr:2 row_mask:0xf bank_mask:0xf bound_ctrl:1
	v_mov_b32_dpp v0, v60 row_bcast:15 row_mask:0xa bank_mask:0xf
	v_add_f32_e32 v83, v60, v0
	s_waitcnt lgkmcnt(0)
	s_nop 1
	v_subrev_f32_dpp v0, v78, v78 row_newbcast:15 row_mask:0x5 bank_mask:0xf
	v_subrev_f32_dpp v0, v78, v78 row_bcast:15 row_mask:0xa bank_mask:0xf
	v_med3_f32 v0, v0, s69, v189
	v_add_f32_dpp v61, v61, v61 row_shr:4 row_mask:0xf bank_mask:0xf bound_ctrl:1
	v_mul_f32_e32 v0, 0x3fb8aa3b, v0
	v_exp_f32_e32 v20, v0
	v_add_f32_dpp v61, v61, v61 row_shr:8 row_mask:0xf bank_mask:0xf bound_ctrl:1
	v_mov_b32_e32 v0, v2
	s_nop 1
	v_subrev_f32_dpp v1, v79, v79 row_newbcast:15 row_mask:0x5 bank_mask:0xf
	v_subrev_f32_dpp v1, v79, v79 row_bcast:15 row_mask:0xa bank_mask:0xf
	v_med3_f32 v1, v1, s69, v189
	v_mov_b32_dpp v0, v61 row_bcast:15 row_mask:0xa bank_mask:0xf
	v_add_f32_e32 v84, v61, v0
	v_mul_f32_e32 v1, 0x3fb8aa3b, v1
	v_exp_f32_e32 v21, v1
	s_nop 1
	v_subrev_f32_dpp v22, v80, v80 row_newbcast:15 row_mask:0x5 bank_mask:0xf
	v_subrev_f32_dpp v22, v80, v80 row_bcast:15 row_mask:0xa bank_mask:0xf
	s_nop 1
	v_subrev_f32_dpp v1, v81, v81 row_newbcast:15 row_mask:0x5 bank_mask:0xf
	v_subrev_f32_dpp v1, v81, v81 row_bcast:15 row_mask:0xa bank_mask:0xf
	s_nop 1
	v_subrev_f32_dpp v62, v77, v77 row_newbcast:15 row_mask:0x5 bank_mask:0xf
	v_subrev_f32_dpp v62, v77, v77 row_bcast:15 row_mask:0xa bank_mask:0xf
	s_nop 1
	v_subrev_f32_dpp v63, v82, v82 row_newbcast:15 row_mask:0x5 bank_mask:0xf
	v_subrev_f32_dpp v63, v82, v82 row_bcast:15 row_mask:0xa bank_mask:0xf
	s_nop 1
	v_subrev_f32_dpp v64, v83, v83 row_newbcast:15 row_mask:0x5 bank_mask:0xf
	v_subrev_f32_dpp v64, v83, v83 row_bcast:15 row_mask:0xa bank_mask:0xf
	s_nop 1
	v_subrev_f32_dpp v65, v84, v84 row_newbcast:15 row_mask:0x5 bank_mask:0xf
	v_subrev_f32_dpp v65, v84, v84 row_bcast:15 row_mask:0xa bank_mask:0xf
	v_med3_f32 v22, v22, s69, v189
	v_med3_f32 v1, v1, s69, v189
	v_med3_f32 v62, v62, s69, v189
	v_med3_f32 v63, v63, s69, v189
	v_med3_f32 v64, v64, s69, v189
	v_med3_f32 v65, v65, s69, v189
	v_mul_f32_e32 v22, 0x3fb8aa3b, v22
	v_mul_f32_e32 v1, 0x3fb8aa3b, v1
	v_mul_f32_e32 v62, 0x3fb8aa3b, v62
	v_mul_f32_e32 v63, 0x3fb8aa3b, v63
	v_mul_f32_e32 v64, 0x3fb8aa3b, v64
	v_mul_f32_e32 v65, 0x3fb8aa3b, v65
	v_exp_f32_e32 v60, v22
	v_exp_f32_e32 v61, v1
	v_exp_f32_e32 v62, v62
	v_exp_f32_e32 v63, v63
	v_exp_f32_e32 v64, v64
	v_exp_f32_e32 v65, v65
	ds_bpermute_b32 v0, v194, v20
	ds_bpermute_b32 v1, v194, v21
	ds_bpermute_b32 v22, v194, v60
	ds_bpermute_b32 v23, v194, v61
	ds_bpermute_b32 v68, v194, v62
	ds_bpermute_b32 v69, v194, v63
	ds_bpermute_b32 v66, v194, v64
	ds_bpermute_b32 v67, v194, v65
	s_and_saveexec_b64 s[16:17], s[6:7]
	s_cbranch_execz .LBB0_853
	v_mul_f32_e32 v78, 0x3fb8aa3b, v78
	v_mul_f32_e32 v79, 0x3fb8aa3b, v79
	v_mul_f32_e32 v80, 0x3fb8aa3b, v80
	v_mul_f32_e32 v81, 0x3fb8aa3b, v81
	v_exp_f32_e32 v78, v78
	v_exp_f32_e32 v79, v79
	v_exp_f32_e32 v80, v80
	v_exp_f32_e32 v81, v81
	v_mul_f32_e32 v77, 0x3fb8aa3b, v77
	ds_write_b128 v203, v[78:81]
	v_exp_f32_e32 v78, v77
	v_mul_f32_e32 v77, 0x3fb8aa3b, v82
	v_exp_f32_e32 v79, v77
	v_mul_f32_e32 v77, 0x3fb8aa3b, v83
	v_exp_f32_e32 v80, v77
	v_mul_f32_e32 v77, 0x3fb8aa3b, v84
	v_exp_f32_e32 v81, v77
	ds_write_b128 v203, v[78:81] offset:16
	s_branch .LBB0_853

.LBB0_869:
	s_and_saveexec_b64 s[80:81], vcc
	s_cbranch_execz .LBB0_873
	s_waitcnt vmcnt(10)
	v_cvt_f32_f16_e32 v0, v32
	v_cvt_f32_f16_sdwa v1, v32 dst_sel:DWORD dst_unused:UNUSED_PAD src0_sel:WORD_1
	v_cvt_f32_f16_e32 v3, v33
	v_cvt_f32_f16_sdwa v32, v33 dst_sel:DWORD dst_unused:UNUSED_PAD src0_sel:WORD_1
	v_add_f32_dpp v0, v0, v0 row_shr:1 row_mask:0xf bank_mask:0xf bound_ctrl:1
	v_add_f32_dpp v1, v1, v1 row_shr:1 row_mask:0xf bank_mask:0xf bound_ctrl:1
	v_mov_b32_e32 v53, v2
	v_add_f32_dpp v0, v0, v0 row_shr:2 row_mask:0xf bank_mask:0xf bound_ctrl:1
	v_add_f32_dpp v1, v1, v1 row_shr:2 row_mask:0xf bank_mask:0xf bound_ctrl:1
	v_cvt_f32_f16_e32 v33, v34
	v_add_f32_dpp v0, v0, v0 row_shr:4 row_mask:0xf bank_mask:0xf bound_ctrl:1
	v_add_f32_dpp v3, v3, v3 row_shr:1 row_mask:0xf bank_mask:0xf bound_ctrl:1
	v_add_f32_dpp v1, v1, v1 row_shr:4 row_mask:0xf bank_mask:0xf bound_ctrl:1
	v_add_f32_dpp v0, v0, v0 row_shr:8 row_mask:0xf bank_mask:0xf bound_ctrl:1
	v_add_f32_dpp v3, v3, v3 row_shr:2 row_mask:0xf bank_mask:0xf bound_ctrl:1
	v_add_f32_dpp v1, v1, v1 row_shr:8 row_mask:0xf bank_mask:0xf bound_ctrl:1
	v_mov_b32_dpp v53, v0 row_bcast:15 row_mask:0xa bank_mask:0xf
	v_add_f32_e32 v62, v0, v53
	v_mov_b32_e32 v0, v2
	v_cvt_f32_f16_sdwa v34, v34 dst_sel:DWORD dst_unused:UNUSED_PAD src0_sel:WORD_1
	v_add_f32_dpp v32, v32, v32 row_shr:1 row_mask:0xf bank_mask:0xf bound_ctrl:1
	v_add_f32_dpp v3, v3, v3 row_shr:4 row_mask:0xf bank_mask:0xf bound_ctrl:1
	v_mov_b32_dpp v0, v1 row_bcast:15 row_mask:0xa bank_mask:0xf
	v_add_f32_dpp v32, v32, v32 row_shr:2 row_mask:0xf bank_mask:0xf bound_ctrl:1
	v_add_f32_dpp v3, v3, v3 row_shr:8 row_mask:0xf bank_mask:0xf bound_ctrl:1
	v_add_f32_e32 v63, v1, v0
	v_mov_b32_e32 v0, v2
	v_cvt_f32_f16_e32 v52, v35
	v_add_f32_dpp v33, v33, v33 row_shr:1 row_mask:0xf bank_mask:0xf bound_ctrl:1
	v_add_f32_dpp v32, v32, v32 row_shr:4 row_mask:0xf bank_mask:0xf bound_ctrl:1
	v_mov_b32_dpp v0, v3 row_bcast:15 row_mask:0xa bank_mask:0xf
	v_add_f32_dpp v33, v33, v33 row_shr:2 row_mask:0xf bank_mask:0xf bound_ctrl:1
	v_add_f32_dpp v32, v32, v32 row_shr:8 row_mask:0xf bank_mask:0xf bound_ctrl:1
	v_add_f32_e32 v64, v3, v0
	v_mov_b32_e32 v0, v2
	v_add_f32_dpp v34, v34, v34 row_shr:1 row_mask:0xf bank_mask:0xf bound_ctrl:1
	v_add_f32_dpp v33, v33, v33 row_shr:4 row_mask:0xf bank_mask:0xf bound_ctrl:1
	v_mov_b32_dpp v0, v32 row_bcast:15 row_mask:0xa bank_mask:0xf
	v_add_f32_dpp v34, v34, v34 row_shr:2 row_mask:0xf bank_mask:0xf bound_ctrl:1
	v_add_f32_dpp v33, v33, v33 row_shr:8 row_mask:0xf bank_mask:0xf bound_ctrl:1
	v_add_f32_e32 v65, v32, v0
	v_mov_b32_e32 v0, v2
	v_add_f32_dpp v52, v52, v52 row_shr:1 row_mask:0xf bank_mask:0xf bound_ctrl:1
	v_add_f32_dpp v34, v34, v34 row_shr:4 row_mask:0xf bank_mask:0xf bound_ctrl:1
	v_mov_b32_dpp v0, v33 row_bcast:15 row_mask:0xa bank_mask:0xf
	v_add_f32_dpp v52, v52, v52 row_shr:2 row_mask:0xf bank_mask:0xf bound_ctrl:1
	v_add_f32_dpp v34, v34, v34 row_shr:8 row_mask:0xf bank_mask:0xf bound_ctrl:1
	v_add_f32_e32 v3, v33, v0
	v_mov_b32_e32 v0, v2
	v_add_f32_dpp v52, v52, v52 row_shr:4 row_mask:0xf bank_mask:0xf bound_ctrl:1
	v_cvt_f32_f16_sdwa v35, v35 dst_sel:DWORD dst_unused:UNUSED_PAD src0_sel:WORD_1
	v_mov_b32_dpp v0, v34 row_bcast:15 row_mask:0xa bank_mask:0xf
	v_add_f32_dpp v52, v52, v52 row_shr:8 row_mask:0xf bank_mask:0xf bound_ctrl:1
	v_add_f32_e32 v66, v34, v0
	v_mov_b32_e32 v0, v2
	v_add_f32_dpp v35, v35, v35 row_shr:1 row_mask:0xf bank_mask:0xf bound_ctrl:1
	v_mov_b32_dpp v0, v52 row_bcast:15 row_mask:0xa bank_mask:0xf
	v_add_f32_e32 v67, v52, v0
	s_waitcnt lgkmcnt(0)
	s_nop 1
	v_subrev_f32_dpp v0, v62, v62 row_newbcast:15 row_mask:0x5 bank_mask:0xf
	v_subrev_f32_dpp v0, v62, v62 row_bcast:15 row_mask:0xa bank_mask:0xf
	v_add_f32_dpp v35, v35, v35 row_shr:2 row_mask:0xf bank_mask:0xf bound_ctrl:1
	v_med3_f32 v0, v0, s69, v189
	v_mul_f32_e32 v0, 0x3fb8aa3b, v0
	v_add_f32_dpp v35, v35, v35 row_shr:4 row_mask:0xf bank_mask:0xf bound_ctrl:1
	v_exp_f32_e32 v32, v0
	v_mov_b32_e32 v0, v2
	v_add_f32_dpp v35, v35, v35 row_shr:8 row_mask:0xf bank_mask:0xf bound_ctrl:1
	s_nop 1
	v_subrev_f32_dpp v1, v63, v63 row_newbcast:15 row_mask:0x5 bank_mask:0xf
	v_subrev_f32_dpp v1, v63, v63 row_bcast:15 row_mask:0xa bank_mask:0xf
	v_mov_b32_dpp v0, v35 row_bcast:15 row_mask:0xa bank_mask:0xf
	v_med3_f32 v1, v1, s69, v189
	v_add_f32_e32 v68, v35, v0
	v_mul_f32_e32 v1, 0x3fb8aa3b, v1
	v_exp_f32_e32 v33, v1
	s_nop 1
	v_subrev_f32_dpp v56, v67, v67 row_newbcast:15 row_mask:0x5 bank_mask:0xf
	v_subrev_f32_dpp v56, v67, v67 row_bcast:15 row_mask:0xa bank_mask:0xf
	v_med3_f32 v56, v56, s69, v189
	v_mul_f32_e32 v56, 0x3fb8aa3b, v56
	s_nop 1
	v_subrev_f32_dpp v34, v64, v64 row_newbcast:15 row_mask:0x5 bank_mask:0xf
	v_subrev_f32_dpp v34, v64, v64 row_bcast:15 row_mask:0xa bank_mask:0xf
	s_nop 1
	v_subrev_f32_dpp v1, v65, v65 row_newbcast:15 row_mask:0x5 bank_mask:0xf
	v_subrev_f32_dpp v1, v65, v65 row_bcast:15 row_mask:0xa bank_mask:0xf
	s_nop 1
	v_subrev_f32_dpp v54, v3, v3 row_newbcast:15 row_mask:0x5 bank_mask:0xf
	v_subrev_f32_dpp v54, v3, v3 row_bcast:15 row_mask:0xa bank_mask:0xf
	s_nop 1
	v_subrev_f32_dpp v55, v66, v66 row_newbcast:15 row_mask:0x5 bank_mask:0xf
	v_subrev_f32_dpp v55, v66, v66 row_bcast:15 row_mask:0xa bank_mask:0xf
	v_exp_f32_e32 v58, v56
	s_nop 1
	v_subrev_f32_dpp v56, v68, v68 row_newbcast:15 row_mask:0x5 bank_mask:0xf
	v_subrev_f32_dpp v56, v68, v68 row_bcast:15 row_mask:0xa bank_mask:0xf
	v_med3_f32 v34, v34, s69, v189
	v_med3_f32 v1, v1, s69, v189
	v_med3_f32 v54, v54, s69, v189
	v_med3_f32 v55, v55, s69, v189
	v_med3_f32 v56, v56, s69, v189
	v_mul_f32_e32 v34, 0x3fb8aa3b, v34
	v_mul_f32_e32 v1, 0x3fb8aa3b, v1
	v_mul_f32_e32 v54, 0x3fb8aa3b, v54
	v_mul_f32_e32 v55, 0x3fb8aa3b, v55
	v_mul_f32_e32 v56, 0x3fb8aa3b, v56
	v_exp_f32_e32 v34, v34
	v_exp_f32_e32 v35, v1
	v_exp_f32_e32 v54, v54
	v_exp_f32_e32 v55, v55
	v_exp_f32_e32 v59, v56
	ds_bpermute_b32 v0, v130, v32
	ds_bpermute_b32 v1, v130, v33
	ds_bpermute_b32 v52, v130, v34
	ds_bpermute_b32 v53, v130, v35
	ds_bpermute_b32 v60, v130, v54
	ds_bpermute_b32 v61, v130, v55
	ds_bpermute_b32 v56, v130, v58
	ds_bpermute_b32 v57, v130, v59
	s_and_saveexec_b64 s[16:17], s[6:7]
	s_cbranch_execz .LBB0_872
	v_mul_f32_e32 v62, 0x3fb8aa3b, v62
	v_mul_f32_e32 v63, 0x3fb8aa3b, v63
	v_mul_f32_e32 v64, 0x3fb8aa3b, v64
	v_mul_f32_e32 v65, 0x3fb8aa3b, v65
	v_exp_f32_e32 v62, v62
	v_exp_f32_e32 v63, v63
	v_exp_f32_e32 v64, v64
	v_exp_f32_e32 v65, v65
	v_mul_f32_e32 v3, 0x3fb8aa3b, v3
	ds_write_b128 v131, v[62:65] offset:34816
	v_exp_f32_e32 v62, v3
	v_mul_f32_e32 v3, 0x3fb8aa3b, v66
	v_exp_f32_e32 v63, v3
	v_mul_f32_e32 v3, 0x3fb8aa3b, v67
	v_exp_f32_e32 v64, v3
	v_mul_f32_e32 v3, 0x3fb8aa3b, v68
	v_exp_f32_e32 v65, v3
	ds_write_b128 v131, v[62:65] offset:34832

.LBB0_873:
	s_or_b64 exec, exec, s[80:81]
	s_add_i32 s78, s35, -1
	s_min_i32 s16, s78, s77
	s_lshl_b32 s16, s16, 5
	v_or_b32_e32 v0, s16, v127
	v_xad_u32 v1, v0, -1, s74
	v_cndmask_b32_e64 v0, v1, v0, s[4:5]
	v_add_u32_e32 v1, s16, v128
	v_xad_u32 v3, v1, -1, s74
	v_add_u32_e32 v0, s73, v0
	s_waitcnt vmcnt(8)
	ds_write_b128 v133, v[8:11] offset:26112
	v_cndmask_b32_e64 v3, v3, v1, s[4:5]
	v_ashrrev_i32_e32 v1, 31, v0
	v_mad_i64_i32 v[8:9], s[16:17], v0, s89, v[116:117]
	global_load_dwordx4 v[24:27], v[8:9], off
	v_lshlrev_b64 v[8:9], 10, v[0:1]
	v_lshl_add_u64 v[8:9], v[118:119], 0, v[8:9]
	v_mad_i64_i32 v[0:1], s[16:17], v0, s89, v[120:121]
	global_load_dwordx4 v[32:35], v[8:9], off
	global_load_dwordx4 v[16:19], v[0:1], off
	v_add_u32_e32 v0, s73, v3
	v_mad_i64_i32 v[0:1], s[16:17], v0, s89, v[122:123]
	global_load_dwordx4 v[8:11], v[0:1], off
	s_waitcnt lgkmcnt(0)
	s_barrier
	ds_read_b64_tr_b16 v[68:69], v134 offset:26112
	ds_read_b64_tr_b16 v[70:71], v134 offset:30464
	ds_read_b64 v[64:65], v135
	ds_read_b64 v[66:67], v135 offset:32
	ds_read_b64 v[52:53], v135 offset:64
	ds_read_b64 v[54:55], v135 offset:96
	ds_read_b64 v[60:61], v135 offset:2304
	ds_read_b64 v[62:63], v135 offset:2336
	ds_read_b64 v[56:57], v135 offset:2368
	ds_read_b64 v[58:59], v135 offset:2400
	ds_read_b64 v[72:73], v136 offset:8704
	ds_read_b64 v[74:75], v136 offset:8736
	ds_read_b64 v[76:77], v136 offset:11008
	ds_read_b64 v[78:79], v136 offset:11040
	ds_read_b64 v[84:85], v136 offset:8768
	ds_read_b64 v[86:87], v136 offset:8800
	ds_read_b64 v[150:151], v136 offset:11072
	ds_read_b64 v[152:153], v136 offset:11104
	s_waitcnt lgkmcnt(6)
	v_mfma_f32_16x16x32_bf16 v[80:83], v[72:75], v[64:67], 0
	v_mov_b32_e32 v0, s93
	s_waitcnt lgkmcnt(4)
	v_mfma_f32_16x16x32_bf16 v[76:79], v[76:79], v[60:63], 0
	s_waitcnt lgkmcnt(2)
	v_mfma_f32_16x16x32_bf16 v[80:83], v[84:87], v[52:55], v[80:83]
	s_waitcnt lgkmcnt(0)
	v_mfma_f32_16x16x32_bf16 v[76:79], v[150:153], v[56:59], v[76:79]
	v_mov_b32_e32 v150, s93
	s_nop 4
	v_cndmask_b32_e64 v0, v80, v0, s[8:9]
	v_cndmask_b32_e64 v0, v0, v80, s[10:11]
	v_mfma_f32_16x16x32_bf16 v[72:75], v[72:75], v[60:63], 0
	v_cndmask_b32_e64 v3, v82, 0, s[12:13]
	v_cndmask_b32_e64 v1, v76, v150, s[8:9]
	v_cndmask_b32_e64 v76, v1, v76, s[10:11]
	v_cndmask_b32_e64 v1, 0, v81, s[10:11]
	v_cndmask_b32_e64 v80, v83, 0, s[14:15]
	v_mfma_f32_16x16x32_bf16 v[72:75], v[84:87], v[56:59], v[72:75]
	v_cvt_pk_bf16_f32 v0, v0, v1
	v_cvt_pk_bf16_f32 v1, v3, v80
	ds_read_b128 v[80:83], v137 offset:35328
	ds_read_b128 v[84:87], v137 offset:35392
	v_cndmask_b32_e64 v77, 0, v77, s[10:11]
	v_cndmask_b32_e64 v78, v78, 0, s[12:13]
	v_cndmask_b32_e64 v79, v79, 0, s[14:15]
	v_mov_b32_e32 v3, v2
	v_cvt_pk_bf16_f32 v72, v72, v73
	v_cvt_pk_bf16_f32 v73, v74, v75
	v_cvt_pk_bf16_f32 v74, v76, v77
	v_cvt_pk_bf16_f32 v75, v78, v79
	v_mfma_f32_16x16x32_bf16 v[76:79], v[68:71], v[0:3], 0
	s_waitcnt lgkmcnt(1)
	v_pk_mul_f32 v[0:1], v[50:51], v[82:83]
	s_waitcnt lgkmcnt(0)
	v_pk_mul_f32 v[86:87], v[46:47], v[86:87]
	v_pk_mul_f32 v[82:83], v[44:45], v[84:85]
	v_pk_mul_f32 v[80:81], v[48:49], v[80:81]
	v_cvt_pk_bf16_f32 v82, v82, v83
	v_cvt_pk_bf16_f32 v83, v86, v87
	ds_read_b128 v[84:87], v137 offset:35456
	ds_read_b128 v[150:153], v137 offset:35520
	v_cvt_pk_bf16_f32 v80, v80, v81
	v_cvt_pk_bf16_f32 v81, v0, v1
	v_mfma_f32_16x16x32_bf16 v[72:75], v[68:71], v[72:75], 0
	s_waitcnt lgkmcnt(1)
	v_pk_mul_f32 v[0:1], v[42:43], v[86:87]
	s_waitcnt lgkmcnt(0)
	v_pk_mul_f32 v[152:153], v[38:39], v[152:153]
	v_pk_mul_f32 v[86:87], v[36:37], v[150:151]
	v_pk_mul_f32 v[84:85], v[40:41], v[84:85]
	v_cvt_pk_bf16_f32 v86, v86, v87
	v_cvt_pk_bf16_f32 v87, v152, v153
	ds_read_b128 v[150:153], v137 offset:34816
	ds_read_b64_tr_b16 v[156:157], v138 offset:19712
	ds_read_b64_tr_b16 v[154:155], v138 offset:17408
	ds_read_b64_tr_b16 v[158:159], v138 offset:17440
	v_cvt_pk_bf16_f32 v84, v84, v85
	s_waitcnt lgkmcnt(3)
	v_pk_mul_f32 v[50:51], v[50:51], v[152:153]
	v_pk_mul_f32 v[48:49], v[48:49], v[150:151]
	ds_read_b128 v[150:153], v137 offset:34880
	ds_read_b64_tr_b16 v[160:161], v138 offset:19744
	v_cvt_pk_bf16_f32 v85, v0, v1
	v_mfma_f32_16x16x32_bf16 v[64:67], v[80:83], v[64:67], v[76:79]
	v_xor_b32_e32 v1, 0xffffffef, v126
	s_waitcnt lgkmcnt(1)
	v_pk_mul_f32 v[46:47], v[46:47], v[152:153]
	v_pk_mul_f32 v[44:45], v[44:45], v[150:151]
	v_mfma_f32_16x16x32_bf16 v[48:51], v[154:157], v[68:71], v[48:51]
	ds_read_b128 v[150:153], v137 offset:34944
	ds_read_b64_tr_b16 v[154:155], v138 offset:17472
	ds_read_b64_tr_b16 v[156:157], v138 offset:19776
	v_add_u32_e32 v0, 16, v126
	v_cndmask_b32_e64 v3, v149, v126, s[4:5]
	v_mfma_f32_16x16x32_bf16 v[60:63], v[80:83], v[60:63], v[72:75]
	s_waitcnt lgkmcnt(2)
	v_pk_mul_f32 v[42:43], v[42:43], v[152:153]
	v_pk_mul_f32 v[40:41], v[40:41], v[150:151]
	v_add_u32_e32 v1, s74, v1
	v_mfma_f32_16x16x32_bf16 v[52:55], v[84:87], v[52:55], v[64:67]
	s_waitcnt lgkmcnt(0)
	v_mfma_f32_16x16x32_bf16 v[40:43], v[154:157], v[68:71], v[40:43]
	ds_read_b128 v[150:153], v137 offset:35008
	ds_read_b64_tr_b16 v[154:155], v138 offset:17504
	ds_read_b64_tr_b16 v[156:157], v138 offset:19808
	s_waitcnt lgkmcnt(2)
	v_pk_mul_f32 v[38:39], v[38:39], v[152:153]
	v_mfma_f32_16x16x32_bf16 v[56:59], v[84:87], v[56:59], v[60:63]
	v_mul_f32_e64 v36, v36, v150
	v_mul_f32_e64 v37, v37, v151
	s_nop 0
	v_cndmask_b32_e64 v60, v1, v0, s[4:5]
	v_cvt_pk_bf16_f32 v1, v54, v55
	v_add_u32_e32 v54, s73, v3
	v_ashrrev_i32_e32 v55, 31, v54
	v_lshlrev_b64 v[54:55], 11, v[54:55]
	v_cvt_pk_bf16_f32 v0, v52, v53
	v_lshl_add_u64 v[54:55], v[124:125], 0, v[54:55]
	v_mfma_f32_16x16x32_bf16 v[44:47], v[158:161], v[68:71], v[44:47]
	global_store_dwordx2 v[54:55], v[0:1], off offset:1024
	v_add_u32_e32 v0, s73, v60
	v_ashrrev_i32_e32 v1, 31, v0
	s_waitcnt lgkmcnt(0)
	v_mfma_f32_16x16x32_bf16 v[36:39], v[154:157], v[68:71], v[36:39]
	v_lshlrev_b64 v[0:1], 11, v[0:1]
	v_cvt_pk_bf16_f32 v52, v56, v57
	v_cvt_pk_bf16_f32 v53, v58, v59
	v_lshl_add_u64 v[0:1], v[124:125], 0, v[0:1]
	global_store_dwordx2 v[0:1], v[52:53], off offset:1024
	s_and_saveexec_b64 s[80:81], vcc
	s_cbranch_execz .LBB0_868
	s_waitcnt vmcnt(10)
	v_cvt_f32_f16_e32 v0, v28
	v_cvt_f32_f16_sdwa v1, v28 dst_sel:DWORD dst_unused:UNUSED_PAD src0_sel:WORD_1
	v_cvt_f32_f16_e32 v3, v29
	v_cvt_f32_f16_sdwa v28, v29 dst_sel:DWORD dst_unused:UNUSED_PAD src0_sel:WORD_1
	v_add_f32_dpp v0, v0, v0 row_shr:1 row_mask:0xf bank_mask:0xf bound_ctrl:1
	v_add_f32_dpp v1, v1, v1 row_shr:1 row_mask:0xf bank_mask:0xf bound_ctrl:1
	v_mov_b32_e32 v53, v2
	v_add_f32_dpp v0, v0, v0 row_shr:2 row_mask:0xf bank_mask:0xf bound_ctrl:1
	v_add_f32_dpp v1, v1, v1 row_shr:2 row_mask:0xf bank_mask:0xf bound_ctrl:1
	v_cvt_f32_f16_e32 v29, v30
	v_add_f32_dpp v0, v0, v0 row_shr:4 row_mask:0xf bank_mask:0xf bound_ctrl:1
	v_add_f32_dpp v3, v3, v3 row_shr:1 row_mask:0xf bank_mask:0xf bound_ctrl:1
	v_add_f32_dpp v1, v1, v1 row_shr:4 row_mask:0xf bank_mask:0xf bound_ctrl:1
	v_add_f32_dpp v0, v0, v0 row_shr:8 row_mask:0xf bank_mask:0xf bound_ctrl:1
	v_add_f32_dpp v3, v3, v3 row_shr:2 row_mask:0xf bank_mask:0xf bound_ctrl:1
	v_add_f32_dpp v1, v1, v1 row_shr:8 row_mask:0xf bank_mask:0xf bound_ctrl:1
	v_mov_b32_dpp v53, v0 row_bcast:15 row_mask:0xa bank_mask:0xf
	v_add_f32_e32 v62, v0, v53
	v_mov_b32_e32 v0, v2
	v_cvt_f32_f16_sdwa v30, v30 dst_sel:DWORD dst_unused:UNUSED_PAD src0_sel:WORD_1
	v_add_f32_dpp v28, v28, v28 row_shr:1 row_mask:0xf bank_mask:0xf bound_ctrl:1
	v_add_f32_dpp v3, v3, v3 row_shr:4 row_mask:0xf bank_mask:0xf bound_ctrl:1
	v_mov_b32_dpp v0, v1 row_bcast:15 row_mask:0xa bank_mask:0xf
	v_add_f32_dpp v28, v28, v28 row_shr:2 row_mask:0xf bank_mask:0xf bound_ctrl:1
	v_add_f32_dpp v3, v3, v3 row_shr:8 row_mask:0xf bank_mask:0xf bound_ctrl:1
	v_add_f32_e32 v63, v1, v0
	v_mov_b32_e32 v0, v2
	v_cvt_f32_f16_e32 v52, v31
	v_add_f32_dpp v29, v29, v29 row_shr:1 row_mask:0xf bank_mask:0xf bound_ctrl:1
	v_add_f32_dpp v28, v28, v28 row_shr:4 row_mask:0xf bank_mask:0xf bound_ctrl:1
	v_mov_b32_dpp v0, v3 row_bcast:15 row_mask:0xa bank_mask:0xf
	v_add_f32_dpp v29, v29, v29 row_shr:2 row_mask:0xf bank_mask:0xf bound_ctrl:1
	v_add_f32_dpp v28, v28, v28 row_shr:8 row_mask:0xf bank_mask:0xf bound_ctrl:1
	v_add_f32_e32 v64, v3, v0
	v_mov_b32_e32 v0, v2
	v_add_f32_dpp v30, v30, v30 row_shr:1 row_mask:0xf bank_mask:0xf bound_ctrl:1
	v_add_f32_dpp v29, v29, v29 row_shr:4 row_mask:0xf bank_mask:0xf bound_ctrl:1
	v_mov_b32_dpp v0, v28 row_bcast:15 row_mask:0xa bank_mask:0xf
	v_add_f32_dpp v30, v30, v30 row_shr:2 row_mask:0xf bank_mask:0xf bound_ctrl:1
	v_add_f32_dpp v29, v29, v29 row_shr:8 row_mask:0xf bank_mask:0xf bound_ctrl:1
	v_add_f32_e32 v65, v28, v0
	v_mov_b32_e32 v0, v2
	v_add_f32_dpp v52, v52, v52 row_shr:1 row_mask:0xf bank_mask:0xf bound_ctrl:1
	v_add_f32_dpp v30, v30, v30 row_shr:4 row_mask:0xf bank_mask:0xf bound_ctrl:1
	v_mov_b32_dpp v0, v29 row_bcast:15 row_mask:0xa bank_mask:0xf
	v_add_f32_dpp v52, v52, v52 row_shr:2 row_mask:0xf bank_mask:0xf bound_ctrl:1
	v_add_f32_dpp v30, v30, v30 row_shr:8 row_mask:0xf bank_mask:0xf bound_ctrl:1
	v_add_f32_e32 v3, v29, v0
	v_mov_b32_e32 v0, v2
	v_add_f32_dpp v52, v52, v52 row_shr:4 row_mask:0xf bank_mask:0xf bound_ctrl:1
	v_cvt_f32_f16_sdwa v31, v31 dst_sel:DWORD dst_unused:UNUSED_PAD src0_sel:WORD_1
	v_mov_b32_dpp v0, v30 row_bcast:15 row_mask:0xa bank_mask:0xf
	v_add_f32_dpp v52, v52, v52 row_shr:8 row_mask:0xf bank_mask:0xf bound_ctrl:1
	v_add_f32_e32 v66, v30, v0
	v_mov_b32_e32 v0, v2
	v_add_f32_dpp v31, v31, v31 row_shr:1 row_mask:0xf bank_mask:0xf bound_ctrl:1
	v_mov_b32_dpp v0, v52 row_bcast:15 row_mask:0xa bank_mask:0xf
	v_add_f32_e32 v67, v52, v0
	s_waitcnt lgkmcnt(0)
	s_nop 1
	v_subrev_f32_dpp v0, v62, v62 row_newbcast:15 row_mask:0x5 bank_mask:0xf
	v_subrev_f32_dpp v0, v62, v62 row_bcast:15 row_mask:0xa bank_mask:0xf
	v_add_f32_dpp v31, v31, v31 row_shr:2 row_mask:0xf bank_mask:0xf bound_ctrl:1
	v_med3_f32 v0, v0, s69, v189
	v_mul_f32_e32 v0, 0x3fb8aa3b, v0
	v_add_f32_dpp v31, v31, v31 row_shr:4 row_mask:0xf bank_mask:0xf bound_ctrl:1
	v_exp_f32_e32 v28, v0
	v_mov_b32_e32 v0, v2
	v_add_f32_dpp v31, v31, v31 row_shr:8 row_mask:0xf bank_mask:0xf bound_ctrl:1
	s_nop 1
	v_subrev_f32_dpp v1, v63, v63 row_newbcast:15 row_mask:0x5 bank_mask:0xf
	v_subrev_f32_dpp v1, v63, v63 row_bcast:15 row_mask:0xa bank_mask:0xf
	v_mov_b32_dpp v0, v31 row_bcast:15 row_mask:0xa bank_mask:0xf
	v_med3_f32 v1, v1, s69, v189
	v_add_f32_e32 v68, v31, v0
	v_mul_f32_e32 v1, 0x3fb8aa3b, v1
	v_exp_f32_e32 v29, v1
	s_nop 1
	v_subrev_f32_dpp v56, v67, v67 row_newbcast:15 row_mask:0x5 bank_mask:0xf
	v_subrev_f32_dpp v56, v67, v67 row_bcast:15 row_mask:0xa bank_mask:0xf
	v_med3_f32 v56, v56, s69, v189
	v_mul_f32_e32 v56, 0x3fb8aa3b, v56
	s_nop 1
	v_subrev_f32_dpp v30, v64, v64 row_newbcast:15 row_mask:0x5 bank_mask:0xf
	v_subrev_f32_dpp v30, v64, v64 row_bcast:15 row_mask:0xa bank_mask:0xf
	s_nop 1
	v_subrev_f32_dpp v1, v65, v65 row_newbcast:15 row_mask:0x5 bank_mask:0xf
	v_subrev_f32_dpp v1, v65, v65 row_bcast:15 row_mask:0xa bank_mask:0xf
	s_nop 1
	v_subrev_f32_dpp v54, v3, v3 row_newbcast:15 row_mask:0x5 bank_mask:0xf
	v_subrev_f32_dpp v54, v3, v3 row_bcast:15 row_mask:0xa bank_mask:0xf
	s_nop 1
	v_subrev_f32_dpp v55, v66, v66 row_newbcast:15 row_mask:0x5 bank_mask:0xf
	v_subrev_f32_dpp v55, v66, v66 row_bcast:15 row_mask:0xa bank_mask:0xf
	v_exp_f32_e32 v58, v56
	s_nop 1
	v_subrev_f32_dpp v56, v68, v68 row_newbcast:15 row_mask:0x5 bank_mask:0xf
	v_subrev_f32_dpp v56, v68, v68 row_bcast:15 row_mask:0xa bank_mask:0xf
	v_med3_f32 v30, v30, s69, v189
	v_med3_f32 v1, v1, s69, v189
	v_med3_f32 v54, v54, s69, v189
	v_med3_f32 v55, v55, s69, v189
	v_med3_f32 v56, v56, s69, v189
	v_mul_f32_e32 v30, 0x3fb8aa3b, v30
	v_mul_f32_e32 v1, 0x3fb8aa3b, v1
	v_mul_f32_e32 v54, 0x3fb8aa3b, v54
	v_mul_f32_e32 v55, 0x3fb8aa3b, v55
	v_mul_f32_e32 v56, 0x3fb8aa3b, v56
	v_exp_f32_e32 v30, v30
	v_exp_f32_e32 v31, v1
	v_exp_f32_e32 v54, v54
	v_exp_f32_e32 v55, v55
	v_exp_f32_e32 v59, v56
	ds_bpermute_b32 v0, v130, v28
	ds_bpermute_b32 v1, v130, v29
	ds_bpermute_b32 v52, v130, v30
	ds_bpermute_b32 v53, v130, v31
	ds_bpermute_b32 v60, v130, v54
	ds_bpermute_b32 v61, v130, v55
	ds_bpermute_b32 v56, v130, v58
	ds_bpermute_b32 v57, v130, v59
	s_and_saveexec_b64 s[16:17], s[6:7]
	s_cbranch_execz .LBB0_867
	v_mul_f32_e32 v62, 0x3fb8aa3b, v62
	v_mul_f32_e32 v63, 0x3fb8aa3b, v63
	v_mul_f32_e32 v64, 0x3fb8aa3b, v64
	v_mul_f32_e32 v65, 0x3fb8aa3b, v65
	v_exp_f32_e32 v62, v62
	v_exp_f32_e32 v63, v63
	v_exp_f32_e32 v64, v64
	v_exp_f32_e32 v65, v65
	v_mul_f32_e32 v3, 0x3fb8aa3b, v3
	ds_write_b128 v139, v[62:65]
	v_exp_f32_e32 v62, v3
	v_mul_f32_e32 v3, 0x3fb8aa3b, v66
	v_exp_f32_e32 v63, v3
	v_mul_f32_e32 v3, 0x3fb8aa3b, v67
	v_exp_f32_e32 v64, v3
	v_mul_f32_e32 v3, 0x3fb8aa3b, v68
	v_exp_f32_e32 v65, v3
	ds_write_b128 v139, v[62:65] offset:16
	s_branch .LBB0_867

.LBB0_883:
	s_and_saveexec_b64 s[56:57], vcc
	s_cbranch_execz .LBB0_887
	s_waitcnt vmcnt(8)
	v_cvt_f32_f16_e32 v60, v24
	v_cvt_f32_f16_sdwa v59, v24 dst_sel:DWORD dst_unused:UNUSED_PAD src0_sel:WORD_1
	v_cvt_f32_f16_e32 v58, v25
	v_cvt_f32_f16_sdwa v57, v25 dst_sel:DWORD dst_unused:UNUSED_PAD src0_sel:WORD_1
	v_add_f32_dpp v0, v60, v60 row_shr:1 row_mask:0xf bank_mask:0xf bound_ctrl:1
	v_add_f32_dpp v1, v59, v59 row_shr:1 row_mask:0xf bank_mask:0xf bound_ctrl:1
	v_mov_b32_e32 v46, 0
	v_add_f32_dpp v0, v0, v0 row_shr:2 row_mask:0xf bank_mask:0xf bound_ctrl:1
	v_add_f32_dpp v1, v1, v1 row_shr:2 row_mask:0xf bank_mask:0xf bound_ctrl:1
	v_cvt_f32_f16_e32 v56, v26
	v_add_f32_dpp v0, v0, v0 row_shr:4 row_mask:0xf bank_mask:0xf bound_ctrl:1
	v_add_f32_dpp v24, v58, v58 row_shr:1 row_mask:0xf bank_mask:0xf bound_ctrl:1
	v_add_f32_dpp v1, v1, v1 row_shr:4 row_mask:0xf bank_mask:0xf bound_ctrl:1
	v_add_f32_dpp v0, v0, v0 row_shr:8 row_mask:0xf bank_mask:0xf bound_ctrl:1
	v_add_f32_dpp v24, v24, v24 row_shr:2 row_mask:0xf bank_mask:0xf bound_ctrl:1
	v_add_f32_dpp v1, v1, v1 row_shr:8 row_mask:0xf bank_mask:0xf bound_ctrl:1
	v_mov_b32_dpp v46, v0 row_bcast:15 row_mask:0xa bank_mask:0xf
	v_add_f32_e32 v62, v0, v46
	v_mov_b32_e32 v0, 0
	v_cvt_f32_f16_sdwa v55, v26 dst_sel:DWORD dst_unused:UNUSED_PAD src0_sel:WORD_1
	v_add_f32_dpp v25, v57, v57 row_shr:1 row_mask:0xf bank_mask:0xf bound_ctrl:1
	v_add_f32_dpp v24, v24, v24 row_shr:4 row_mask:0xf bank_mask:0xf bound_ctrl:1
	v_mov_b32_dpp v0, v1 row_bcast:15 row_mask:0xa bank_mask:0xf
	v_add_f32_dpp v25, v25, v25 row_shr:2 row_mask:0xf bank_mask:0xf bound_ctrl:1
	v_add_f32_dpp v24, v24, v24 row_shr:8 row_mask:0xf bank_mask:0xf bound_ctrl:1
	v_add_f32_e32 v63, v1, v0
	v_mov_b32_e32 v0, 0
	v_cvt_f32_f16_e32 v54, v27
	v_add_f32_dpp v26, v56, v56 row_shr:1 row_mask:0xf bank_mask:0xf bound_ctrl:1
	v_add_f32_dpp v25, v25, v25 row_shr:4 row_mask:0xf bank_mask:0xf bound_ctrl:1
	v_mov_b32_dpp v0, v24 row_bcast:15 row_mask:0xa bank_mask:0xf
	v_add_f32_dpp v26, v26, v26 row_shr:2 row_mask:0xf bank_mask:0xf bound_ctrl:1
	v_add_f32_dpp v25, v25, v25 row_shr:8 row_mask:0xf bank_mask:0xf bound_ctrl:1
	v_add_f32_e32 v64, v24, v0
	v_mov_b32_e32 v0, 0
	v_cvt_f32_f16_sdwa v3, v27 dst_sel:DWORD dst_unused:UNUSED_PAD src0_sel:WORD_1
	v_add_f32_dpp v27, v55, v55 row_shr:1 row_mask:0xf bank_mask:0xf bound_ctrl:1
	v_add_f32_dpp v26, v26, v26 row_shr:4 row_mask:0xf bank_mask:0xf bound_ctrl:1
	v_mov_b32_dpp v0, v25 row_bcast:15 row_mask:0xa bank_mask:0xf
	v_add_f32_dpp v27, v27, v27 row_shr:2 row_mask:0xf bank_mask:0xf bound_ctrl:1
	v_add_f32_dpp v26, v26, v26 row_shr:8 row_mask:0xf bank_mask:0xf bound_ctrl:1
	v_add_f32_e32 v65, v25, v0
	v_mov_b32_e32 v0, 0
	v_add_f32_dpp v44, v54, v54 row_shr:1 row_mask:0xf bank_mask:0xf bound_ctrl:1
	v_add_f32_dpp v27, v27, v27 row_shr:4 row_mask:0xf bank_mask:0xf bound_ctrl:1
	v_mov_b32_dpp v0, v26 row_bcast:15 row_mask:0xa bank_mask:0xf
	v_add_f32_dpp v44, v44, v44 row_shr:2 row_mask:0xf bank_mask:0xf bound_ctrl:1
	v_add_f32_dpp v27, v27, v27 row_shr:8 row_mask:0xf bank_mask:0xf bound_ctrl:1
	v_add_f32_e32 v61, v26, v0
	v_mov_b32_e32 v0, 0
	v_add_f32_dpp v44, v44, v44 row_shr:4 row_mask:0xf bank_mask:0xf bound_ctrl:1
	v_add_f32_dpp v45, v3, v3 row_shr:1 row_mask:0xf bank_mask:0xf bound_ctrl:1
	v_mov_b32_dpp v0, v27 row_bcast:15 row_mask:0xa bank_mask:0xf
	v_add_f32_dpp v44, v44, v44 row_shr:8 row_mask:0xf bank_mask:0xf bound_ctrl:1
	v_add_f32_e32 v66, v27, v0
	v_mov_b32_e32 v0, 0
	v_add_f32_dpp v45, v45, v45 row_shr:2 row_mask:0xf bank_mask:0xf bound_ctrl:1
	v_mov_b32_dpp v0, v44 row_bcast:15 row_mask:0xa bank_mask:0xf
	v_add_f32_e32 v67, v44, v0
	s_waitcnt lgkmcnt(0)
	s_nop 1
	v_subrev_f32_dpp v0, v62, v62 row_newbcast:15 row_mask:0x5 bank_mask:0xf
	v_subrev_f32_dpp v0, v62, v62 row_bcast:15 row_mask:0xa bank_mask:0xf
	v_med3_f32 v0, v0, s69, v189
	v_add_f32_dpp v45, v45, v45 row_shr:4 row_mask:0xf bank_mask:0xf bound_ctrl:1
	v_mul_f32_e32 v0, 0x3fb8aa3b, v0
	v_exp_f32_e32 v24, v0
	v_add_f32_dpp v45, v45, v45 row_shr:8 row_mask:0xf bank_mask:0xf bound_ctrl:1
	v_mov_b32_e32 v0, 0
	s_nop 1
	v_subrev_f32_dpp v1, v63, v63 row_newbcast:15 row_mask:0x5 bank_mask:0xf
	v_subrev_f32_dpp v1, v63, v63 row_bcast:15 row_mask:0xa bank_mask:0xf
	v_med3_f32 v1, v1, s69, v189
	v_mov_b32_dpp v0, v45 row_bcast:15 row_mask:0xa bank_mask:0xf
	v_add_f32_e32 v68, v45, v0
	v_mul_f32_e32 v1, 0x3fb8aa3b, v1
	v_exp_f32_e32 v25, v1
	s_nop 1
	v_subrev_f32_dpp v26, v64, v64 row_newbcast:15 row_mask:0x5 bank_mask:0xf
	v_subrev_f32_dpp v26, v64, v64 row_bcast:15 row_mask:0xa bank_mask:0xf
	s_nop 1
	v_subrev_f32_dpp v1, v65, v65 row_newbcast:15 row_mask:0x5 bank_mask:0xf
	v_subrev_f32_dpp v1, v65, v65 row_bcast:15 row_mask:0xa bank_mask:0xf
	s_nop 1
	v_subrev_f32_dpp v46, v61, v61 row_newbcast:15 row_mask:0x5 bank_mask:0xf
	v_subrev_f32_dpp v46, v61, v61 row_bcast:15 row_mask:0xa bank_mask:0xf
	s_nop 1
	v_subrev_f32_dpp v47, v66, v66 row_newbcast:15 row_mask:0x5 bank_mask:0xf
	v_subrev_f32_dpp v47, v66, v66 row_bcast:15 row_mask:0xa bank_mask:0xf
	s_nop 1
	v_subrev_f32_dpp v48, v67, v67 row_newbcast:15 row_mask:0x5 bank_mask:0xf
	v_subrev_f32_dpp v48, v67, v67 row_bcast:15 row_mask:0xa bank_mask:0xf
	s_nop 1
	v_subrev_f32_dpp v49, v68, v68 row_newbcast:15 row_mask:0x5 bank_mask:0xf
	v_subrev_f32_dpp v49, v68, v68 row_bcast:15 row_mask:0xa bank_mask:0xf
	v_med3_f32 v26, v26, s69, v189
	v_med3_f32 v1, v1, s69, v189
	v_med3_f32 v46, v46, s69, v189
	v_med3_f32 v47, v47, s69, v189
	v_med3_f32 v48, v48, s69, v189
	v_med3_f32 v49, v49, s69, v189
	v_mul_f32_e32 v26, 0x3fb8aa3b, v26
	v_mul_f32_e32 v1, 0x3fb8aa3b, v1
	v_mul_f32_e32 v46, 0x3fb8aa3b, v46
	v_mul_f32_e32 v47, 0x3fb8aa3b, v47
	v_mul_f32_e32 v48, 0x3fb8aa3b, v48
	v_mul_f32_e32 v49, 0x3fb8aa3b, v49
	v_exp_f32_e32 v44, v26
	v_exp_f32_e32 v45, v1
	v_exp_f32_e32 v46, v46
	v_exp_f32_e32 v47, v47
	v_exp_f32_e32 v48, v48
	v_exp_f32_e32 v49, v49
	ds_bpermute_b32 v0, v92, v24
	ds_bpermute_b32 v1, v92, v25
	ds_bpermute_b32 v26, v92, v44
	ds_bpermute_b32 v27, v92, v45
	ds_bpermute_b32 v52, v92, v46
	ds_bpermute_b32 v53, v92, v47
	ds_bpermute_b32 v50, v92, v48
	ds_bpermute_b32 v51, v92, v49
	s_and_saveexec_b64 s[16:17], s[6:7]
	s_cbranch_execz .LBB0_886
	v_mul_f32_e32 v62, 0x3fb8aa3b, v62
	v_mul_f32_e32 v63, 0x3fb8aa3b, v63
	v_mul_f32_e32 v64, 0x3fb8aa3b, v64
	v_mul_f32_e32 v65, 0x3fb8aa3b, v65
	v_exp_f32_e32 v62, v62
	v_exp_f32_e32 v63, v63
	v_exp_f32_e32 v64, v64
	v_exp_f32_e32 v65, v65
	v_mul_f32_e32 v61, 0x3fb8aa3b, v61
	ds_write_b128 v93, v[62:65] offset:34816
	v_exp_f32_e32 v62, v61
	v_mul_f32_e32 v61, 0x3fb8aa3b, v66
	v_exp_f32_e32 v63, v61
	v_mul_f32_e32 v61, 0x3fb8aa3b, v67
	v_exp_f32_e32 v64, v61
	v_mul_f32_e32 v61, 0x3fb8aa3b, v68
	v_exp_f32_e32 v65, v61
	ds_write_b128 v93, v[62:65] offset:34832

.LBB0_887:
	s_or_b64 exec, exec, s[56:57]
	s_add_i32 s58, s28, -1
	s_min_i32 s16, s58, s35
	s_lshl_b32 s16, s16, 5
	v_or_b32_e32 v0, s16, v89
	v_xad_u32 v1, v0, -1, s74
	v_cndmask_b32_e64 v0, v1, v0, s[4:5]
	v_add_u32_e32 v1, s16, v90
	v_xad_u32 v3, v1, -1, s74
	v_add_u32_e32 v0, s73, v0
	v_cndmask_b32_e64 v3, v3, v1, s[4:5]
	v_ashrrev_i32_e32 v1, 31, v0
	s_waitcnt vmcnt(7)
	ds_write_b128 v95, v[8:11] offset:26112
	v_mad_i64_i32 v[8:9], s[16:17], v0, s89, v[80:81]
	v_lshlrev_b64 v[0:1], 11, v[0:1]
	v_lshl_add_u64 v[0:1], v[82:83], 0, v[0:1]
	global_load_dwordx4 v[16:19], v[8:9], off
	global_load_dwordx4 v[24:27], v[0:1], off
	v_add_u32_e32 v0, s73, v3
	v_mad_i64_i32 v[0:1], s[16:17], v0, s89, v[84:85]
	global_load_dwordx4 v[8:11], v[0:1], off
	s_waitcnt lgkmcnt(0)
	s_barrier
	ds_read_b64_tr_b16 v[60:61], v96 offset:26112
	ds_read_b64_tr_b16 v[62:63], v96 offset:30464
	ds_read_b64 v[56:57], v97
	ds_read_b64 v[58:59], v97 offset:32
	ds_read_b64 v[44:45], v97 offset:64
	ds_read_b64 v[46:47], v97 offset:96
	ds_read_b64 v[52:53], v97 offset:2304
	ds_read_b64 v[54:55], v97 offset:2336
	ds_read_b64 v[48:49], v97 offset:2368
	ds_read_b64 v[50:51], v97 offset:2400
	ds_read_b64 v[64:65], v98 offset:8704
	ds_read_b64 v[66:67], v98 offset:8736
	ds_read_b64 v[68:69], v98 offset:11008
	ds_read_b64 v[70:71], v98 offset:11040
	ds_read_b64 v[76:77], v98 offset:8768
	ds_read_b64 v[78:79], v98 offset:8800
	ds_read_b64 v[112:113], v98 offset:11072
	ds_read_b64 v[114:115], v98 offset:11104
	s_waitcnt lgkmcnt(6)
	v_mfma_f32_16x16x32_bf16 v[72:75], v[64:67], v[56:59], 0
	v_mov_b32_e32 v0, s93
	s_waitcnt lgkmcnt(4)
	v_mfma_f32_16x16x32_bf16 v[68:71], v[68:71], v[52:55], 0
	s_waitcnt lgkmcnt(2)
	v_mfma_f32_16x16x32_bf16 v[72:75], v[76:79], v[44:47], v[72:75]
	s_waitcnt lgkmcnt(0)
	v_mfma_f32_16x16x32_bf16 v[68:71], v[112:115], v[48:51], v[68:71]
	v_mov_b32_e32 v112, s93
	s_nop 4
	v_cndmask_b32_e64 v0, v72, v0, s[8:9]
	v_cndmask_b32_e64 v0, v0, v72, s[10:11]
	v_mfma_f32_16x16x32_bf16 v[64:67], v[64:67], v[52:55], 0
	v_cndmask_b32_e64 v3, v74, 0, s[12:13]
	v_cndmask_b32_e64 v1, v68, v112, s[8:9]
	v_cndmask_b32_e64 v68, v1, v68, s[10:11]
	v_cndmask_b32_e64 v1, 0, v73, s[10:11]
	v_cndmask_b32_e64 v72, v75, 0, s[14:15]
	v_mfma_f32_16x16x32_bf16 v[64:67], v[76:79], v[48:51], v[64:67]
	v_cvt_pk_bf16_f32 v0, v0, v1
	v_cvt_pk_bf16_f32 v1, v3, v72
	ds_read_b128 v[72:75], v99 offset:35328
	ds_read_b128 v[76:79], v99 offset:35392
	v_cndmask_b32_e64 v69, 0, v69, s[10:11]
	v_cndmask_b32_e64 v70, v70, 0, s[12:13]
	v_cndmask_b32_e64 v71, v71, 0, s[14:15]
	v_mov_b32_e32 v3, v2
	v_cvt_pk_bf16_f32 v64, v64, v65
	v_cvt_pk_bf16_f32 v65, v66, v67
	v_cvt_pk_bf16_f32 v66, v68, v69
	v_cvt_pk_bf16_f32 v67, v70, v71
	v_mfma_f32_16x16x32_bf16 v[68:71], v[60:63], v[0:3], 0
	s_waitcnt lgkmcnt(1)
	v_pk_mul_f32 v[0:1], v[42:43], v[74:75]
	s_waitcnt lgkmcnt(0)
	v_pk_mul_f32 v[78:79], v[38:39], v[78:79]
	v_pk_mul_f32 v[74:75], v[36:37], v[76:77]
	v_pk_mul_f32 v[72:73], v[40:41], v[72:73]
	v_cvt_pk_bf16_f32 v74, v74, v75
	v_cvt_pk_bf16_f32 v75, v78, v79
	ds_read_b128 v[76:79], v99 offset:35456
	ds_read_b128 v[112:115], v99 offset:35520
	v_cvt_pk_bf16_f32 v72, v72, v73
	v_cvt_pk_bf16_f32 v73, v0, v1
	v_mfma_f32_16x16x32_bf16 v[64:67], v[60:63], v[64:67], 0
	s_waitcnt lgkmcnt(1)
	v_pk_mul_f32 v[0:1], v[30:31], v[78:79]
	s_waitcnt lgkmcnt(0)
	v_pk_mul_f32 v[114:115], v[34:35], v[114:115]
	v_pk_mul_f32 v[78:79], v[32:33], v[112:113]
	v_pk_mul_f32 v[76:77], v[28:29], v[76:77]
	v_cvt_pk_bf16_f32 v78, v78, v79
	v_cvt_pk_bf16_f32 v79, v114, v115
	ds_read_b128 v[112:115], v99 offset:34816
	ds_read_b64_tr_b16 v[118:119], v100 offset:19712
	ds_read_b64_tr_b16 v[116:117], v100 offset:17408
	ds_read_b64_tr_b16 v[120:121], v100 offset:17440
	v_cvt_pk_bf16_f32 v76, v76, v77
	s_waitcnt lgkmcnt(3)
	v_pk_mul_f32 v[42:43], v[42:43], v[114:115]
	v_pk_mul_f32 v[40:41], v[40:41], v[112:113]
	ds_read_b128 v[112:115], v99 offset:34880
	ds_read_b64_tr_b16 v[122:123], v100 offset:19744
	v_cvt_pk_bf16_f32 v77, v0, v1
	v_mfma_f32_16x16x32_bf16 v[56:59], v[72:75], v[56:59], v[68:71]
	v_xor_b32_e32 v1, 0xffffffef, v88
	s_waitcnt lgkmcnt(1)
	v_pk_mul_f32 v[38:39], v[38:39], v[114:115]
	v_pk_mul_f32 v[36:37], v[36:37], v[112:113]
	v_mfma_f32_16x16x32_bf16 v[40:43], v[116:119], v[60:63], v[40:43]
	ds_read_b128 v[112:115], v99 offset:34944
	ds_read_b64_tr_b16 v[116:117], v100 offset:17472
	ds_read_b64_tr_b16 v[118:119], v100 offset:19776
	v_add_u32_e32 v0, 16, v88
	v_cndmask_b32_e64 v3, v111, v88, s[4:5]
	v_mfma_f32_16x16x32_bf16 v[52:55], v[72:75], v[52:55], v[64:67]
	s_waitcnt lgkmcnt(2)
	v_pk_mul_f32 v[30:31], v[30:31], v[114:115]
	v_pk_mul_f32 v[28:29], v[28:29], v[112:113]
	v_add_u32_e32 v1, s74, v1
	v_mfma_f32_16x16x32_bf16 v[44:47], v[76:79], v[44:47], v[56:59]
	s_waitcnt lgkmcnt(0)
	v_mfma_f32_16x16x32_bf16 v[28:31], v[116:119], v[60:63], v[28:31]
	ds_read_b128 v[112:115], v99 offset:35008
	ds_read_b64_tr_b16 v[116:117], v100 offset:17504
	ds_read_b64_tr_b16 v[118:119], v100 offset:19808
	s_waitcnt lgkmcnt(2)
	v_pk_mul_f32 v[34:35], v[34:35], v[114:115]
	v_mfma_f32_16x16x32_bf16 v[48:51], v[76:79], v[48:51], v[52:55]
	v_mul_f32_e64 v32, v32, v112
	v_mul_f32_e64 v33, v33, v113
	s_nop 0
	v_cndmask_b32_e64 v52, v1, v0, s[4:5]
	v_cvt_pk_bf16_f32 v1, v46, v47
	v_add_u32_e32 v46, s73, v3
	v_ashrrev_i32_e32 v47, 31, v46
	v_lshlrev_b64 v[46:47], 11, v[46:47]
	v_cvt_pk_bf16_f32 v0, v44, v45
	v_lshl_add_u64 v[46:47], v[86:87], 0, v[46:47]
	v_mfma_f32_16x16x32_bf16 v[36:39], v[120:123], v[60:63], v[36:39]
	global_store_dwordx2 v[46:47], v[0:1], off
	v_add_u32_e32 v0, s73, v52
	v_ashrrev_i32_e32 v1, 31, v0
	s_waitcnt lgkmcnt(0)
	v_mfma_f32_16x16x32_bf16 v[32:35], v[116:119], v[60:63], v[32:35]
	v_lshlrev_b64 v[0:1], 11, v[0:1]
	v_cvt_pk_bf16_f32 v44, v48, v49
	v_cvt_pk_bf16_f32 v45, v50, v51
	v_lshl_add_u64 v[0:1], v[86:87], 0, v[0:1]
	global_store_dwordx2 v[0:1], v[44:45], off
	s_and_saveexec_b64 s[56:57], vcc
	s_cbranch_execz .LBB0_882
	s_waitcnt vmcnt(8)
	v_cvt_f32_f16_e32 v60, v20
	v_cvt_f32_f16_sdwa v59, v20 dst_sel:DWORD dst_unused:UNUSED_PAD src0_sel:WORD_1
	v_cvt_f32_f16_e32 v58, v21
	v_cvt_f32_f16_sdwa v57, v21 dst_sel:DWORD dst_unused:UNUSED_PAD src0_sel:WORD_1
	v_add_f32_dpp v0, v60, v60 row_shr:1 row_mask:0xf bank_mask:0xf bound_ctrl:1
	v_add_f32_dpp v1, v59, v59 row_shr:1 row_mask:0xf bank_mask:0xf bound_ctrl:1
	v_mov_b32_e32 v46, v2
	v_add_f32_dpp v0, v0, v0 row_shr:2 row_mask:0xf bank_mask:0xf bound_ctrl:1
	v_add_f32_dpp v1, v1, v1 row_shr:2 row_mask:0xf bank_mask:0xf bound_ctrl:1
	v_cvt_f32_f16_e32 v56, v22
	v_add_f32_dpp v0, v0, v0 row_shr:4 row_mask:0xf bank_mask:0xf bound_ctrl:1
	v_add_f32_dpp v20, v58, v58 row_shr:1 row_mask:0xf bank_mask:0xf bound_ctrl:1
	v_add_f32_dpp v1, v1, v1 row_shr:4 row_mask:0xf bank_mask:0xf bound_ctrl:1
	v_add_f32_dpp v0, v0, v0 row_shr:8 row_mask:0xf bank_mask:0xf bound_ctrl:1
	v_add_f32_dpp v20, v20, v20 row_shr:2 row_mask:0xf bank_mask:0xf bound_ctrl:1
	v_add_f32_dpp v1, v1, v1 row_shr:8 row_mask:0xf bank_mask:0xf bound_ctrl:1
	v_mov_b32_dpp v46, v0 row_bcast:15 row_mask:0xa bank_mask:0xf
	v_add_f32_e32 v62, v0, v46
	v_mov_b32_e32 v0, v2
	v_cvt_f32_f16_sdwa v55, v22 dst_sel:DWORD dst_unused:UNUSED_PAD src0_sel:WORD_1
	v_add_f32_dpp v21, v57, v57 row_shr:1 row_mask:0xf bank_mask:0xf bound_ctrl:1
	v_add_f32_dpp v20, v20, v20 row_shr:4 row_mask:0xf bank_mask:0xf bound_ctrl:1
	v_mov_b32_dpp v0, v1 row_bcast:15 row_mask:0xa bank_mask:0xf
	v_add_f32_dpp v21, v21, v21 row_shr:2 row_mask:0xf bank_mask:0xf bound_ctrl:1
	v_add_f32_dpp v20, v20, v20 row_shr:8 row_mask:0xf bank_mask:0xf bound_ctrl:1
	v_add_f32_e32 v63, v1, v0
	v_mov_b32_e32 v0, v2
	v_cvt_f32_f16_e32 v54, v23
	v_add_f32_dpp v22, v56, v56 row_shr:1 row_mask:0xf bank_mask:0xf bound_ctrl:1
	v_add_f32_dpp v21, v21, v21 row_shr:4 row_mask:0xf bank_mask:0xf bound_ctrl:1
	v_mov_b32_dpp v0, v20 row_bcast:15 row_mask:0xa bank_mask:0xf
	v_add_f32_dpp v22, v22, v22 row_shr:2 row_mask:0xf bank_mask:0xf bound_ctrl:1
	v_add_f32_dpp v21, v21, v21 row_shr:8 row_mask:0xf bank_mask:0xf bound_ctrl:1
	v_add_f32_e32 v64, v20, v0
	v_mov_b32_e32 v0, v2
	v_cvt_f32_f16_sdwa v3, v23 dst_sel:DWORD dst_unused:UNUSED_PAD src0_sel:WORD_1
	v_add_f32_dpp v23, v55, v55 row_shr:1 row_mask:0xf bank_mask:0xf bound_ctrl:1
	v_add_f32_dpp v22, v22, v22 row_shr:4 row_mask:0xf bank_mask:0xf bound_ctrl:1
	v_mov_b32_dpp v0, v21 row_bcast:15 row_mask:0xa bank_mask:0xf
	v_add_f32_dpp v23, v23, v23 row_shr:2 row_mask:0xf bank_mask:0xf bound_ctrl:1
	v_add_f32_dpp v22, v22, v22 row_shr:8 row_mask:0xf bank_mask:0xf bound_ctrl:1
	v_add_f32_e32 v65, v21, v0
	v_mov_b32_e32 v0, v2
	v_add_f32_dpp v44, v54, v54 row_shr:1 row_mask:0xf bank_mask:0xf bound_ctrl:1
	v_add_f32_dpp v23, v23, v23 row_shr:4 row_mask:0xf bank_mask:0xf bound_ctrl:1
	v_mov_b32_dpp v0, v22 row_bcast:15 row_mask:0xa bank_mask:0xf
	v_add_f32_dpp v44, v44, v44 row_shr:2 row_mask:0xf bank_mask:0xf bound_ctrl:1
	v_add_f32_dpp v23, v23, v23 row_shr:8 row_mask:0xf bank_mask:0xf bound_ctrl:1
	v_add_f32_e32 v61, v22, v0
	v_mov_b32_e32 v0, v2
	v_add_f32_dpp v44, v44, v44 row_shr:4 row_mask:0xf bank_mask:0xf bound_ctrl:1
	v_add_f32_dpp v45, v3, v3 row_shr:1 row_mask:0xf bank_mask:0xf bound_ctrl:1
	v_mov_b32_dpp v0, v23 row_bcast:15 row_mask:0xa bank_mask:0xf
	v_add_f32_dpp v44, v44, v44 row_shr:8 row_mask:0xf bank_mask:0xf bound_ctrl:1
	v_add_f32_e32 v66, v23, v0
	v_mov_b32_e32 v0, v2
	v_add_f32_dpp v45, v45, v45 row_shr:2 row_mask:0xf bank_mask:0xf bound_ctrl:1
	v_mov_b32_dpp v0, v44 row_bcast:15 row_mask:0xa bank_mask:0xf
	v_add_f32_e32 v67, v44, v0
	s_waitcnt lgkmcnt(0)
	s_nop 1
	v_subrev_f32_dpp v0, v62, v62 row_newbcast:15 row_mask:0x5 bank_mask:0xf
	v_subrev_f32_dpp v0, v62, v62 row_bcast:15 row_mask:0xa bank_mask:0xf
	v_med3_f32 v0, v0, s69, v189
	v_add_f32_dpp v45, v45, v45 row_shr:4 row_mask:0xf bank_mask:0xf bound_ctrl:1
	v_mul_f32_e32 v0, 0x3fb8aa3b, v0
	v_exp_f32_e32 v20, v0
	v_add_f32_dpp v45, v45, v45 row_shr:8 row_mask:0xf bank_mask:0xf bound_ctrl:1
	v_mov_b32_e32 v0, v2
	s_nop 1
	v_subrev_f32_dpp v1, v63, v63 row_newbcast:15 row_mask:0x5 bank_mask:0xf
	v_subrev_f32_dpp v1, v63, v63 row_bcast:15 row_mask:0xa bank_mask:0xf
	v_med3_f32 v1, v1, s69, v189
	v_mov_b32_dpp v0, v45 row_bcast:15 row_mask:0xa bank_mask:0xf
	v_add_f32_e32 v68, v45, v0
	v_mul_f32_e32 v1, 0x3fb8aa3b, v1
	v_exp_f32_e32 v21, v1
	s_nop 1
	v_subrev_f32_dpp v22, v64, v64 row_newbcast:15 row_mask:0x5 bank_mask:0xf
	v_subrev_f32_dpp v22, v64, v64 row_bcast:15 row_mask:0xa bank_mask:0xf
	s_nop 1
	v_subrev_f32_dpp v1, v65, v65 row_newbcast:15 row_mask:0x5 bank_mask:0xf
	v_subrev_f32_dpp v1, v65, v65 row_bcast:15 row_mask:0xa bank_mask:0xf
	s_nop 1
	v_subrev_f32_dpp v46, v61, v61 row_newbcast:15 row_mask:0x5 bank_mask:0xf
	v_subrev_f32_dpp v46, v61, v61 row_bcast:15 row_mask:0xa bank_mask:0xf
	s_nop 1
	v_subrev_f32_dpp v47, v66, v66 row_newbcast:15 row_mask:0x5 bank_mask:0xf
	v_subrev_f32_dpp v47, v66, v66 row_bcast:15 row_mask:0xa bank_mask:0xf
	s_nop 1
	v_subrev_f32_dpp v48, v67, v67 row_newbcast:15 row_mask:0x5 bank_mask:0xf
	v_subrev_f32_dpp v48, v67, v67 row_bcast:15 row_mask:0xa bank_mask:0xf
	s_nop 1
	v_subrev_f32_dpp v49, v68, v68 row_newbcast:15 row_mask:0x5 bank_mask:0xf
	v_subrev_f32_dpp v49, v68, v68 row_bcast:15 row_mask:0xa bank_mask:0xf
	v_med3_f32 v22, v22, s69, v189
	v_med3_f32 v1, v1, s69, v189
	v_med3_f32 v46, v46, s69, v189
	v_med3_f32 v47, v47, s69, v189
	v_med3_f32 v48, v48, s69, v189
	v_med3_f32 v49, v49, s69, v189
	v_mul_f32_e32 v22, 0x3fb8aa3b, v22
	v_mul_f32_e32 v1, 0x3fb8aa3b, v1
	v_mul_f32_e32 v46, 0x3fb8aa3b, v46
	v_mul_f32_e32 v47, 0x3fb8aa3b, v47
	v_mul_f32_e32 v48, 0x3fb8aa3b, v48
	v_mul_f32_e32 v49, 0x3fb8aa3b, v49
	v_exp_f32_e32 v44, v22
	v_exp_f32_e32 v45, v1
	v_exp_f32_e32 v46, v46
	v_exp_f32_e32 v47, v47
	v_exp_f32_e32 v48, v48
	v_exp_f32_e32 v49, v49
	ds_bpermute_b32 v0, v92, v20
	ds_bpermute_b32 v1, v92, v21
	ds_bpermute_b32 v22, v92, v44
	ds_bpermute_b32 v23, v92, v45
	ds_bpermute_b32 v52, v92, v46
	ds_bpermute_b32 v53, v92, v47
	ds_bpermute_b32 v50, v92, v48
	ds_bpermute_b32 v51, v92, v49
	s_and_saveexec_b64 s[16:17], s[6:7]
	s_cbranch_execz .LBB0_881
	v_mul_f32_e32 v62, 0x3fb8aa3b, v62
	v_mul_f32_e32 v63, 0x3fb8aa3b, v63
	v_mul_f32_e32 v64, 0x3fb8aa3b, v64
	v_mul_f32_e32 v65, 0x3fb8aa3b, v65
	v_exp_f32_e32 v62, v62
	v_exp_f32_e32 v63, v63
	v_exp_f32_e32 v64, v64
	v_exp_f32_e32 v65, v65
	v_mul_f32_e32 v61, 0x3fb8aa3b, v61
	ds_write_b128 v101, v[62:65]
	v_exp_f32_e32 v62, v61
	v_mul_f32_e32 v61, 0x3fb8aa3b, v66
	v_exp_f32_e32 v63, v61
	v_mul_f32_e32 v61, 0x3fb8aa3b, v67
	v_exp_f32_e32 v64, v61
	v_mul_f32_e32 v61, 0x3fb8aa3b, v68
	v_exp_f32_e32 v65, v61
	ds_write_b128 v101, v[62:65] offset:16
	s_branch .LBB0_881
